# row sum-of-squares quarter-row reductions in the three residual epilogues by permlane16/32 swaps instead of ds_bpermute (63 sites)
# speedup vs baseline: 1.0004x; 1.0004x over previous
.LBB0_320:
	v_lshl_or_b32 v198, s60, 8, v222
	v_lshl_add_u32 v214, s61, 8, v220
	v_ashrrev_i32_e32 v199, 31, v198
	v_lshlrev_b64 v[216:217], 1, v[198:199]
	v_ashrrev_i32_e32 v215, 31, v214
	v_lshl_add_u64 v[0:1], s[64:65], 0, v[216:217]
	v_lshlrev_b64 v[218:219], 11, v[214:215]
	v_lshl_add_u64 v[2:3], v[0:1], 0, v[218:219]
	global_load_dwordx4 v[224:227], v[2:3], off
	global_load_dwordx4 v[228:231], v[2:3], off offset:256
	v_or_b32_e32 v2, 16, v214
	v_ashrrev_i32_e32 v3, 31, v2
	v_lshlrev_b64 v[212:213], 11, v[2:3]
	v_lshl_add_u64 v[2:3], v[0:1], 0, v[212:213]
	global_load_dwordx4 v[180:183], v[2:3], off
	global_load_dwordx4 v[176:179], v[2:3], off offset:256
	v_or_b32_e32 v2, 32, v214
	v_ashrrev_i32_e32 v3, 31, v2
	v_lshlrev_b64 v[210:211], 11, v[2:3]
	v_lshl_add_u64 v[2:3], v[0:1], 0, v[210:211]
	global_load_dwordx4 v[172:175], v[2:3], off
	global_load_dwordx4 v[168:171], v[2:3], off offset:256
	v_or_b32_e32 v2, 48, v214
	v_ashrrev_i32_e32 v3, 31, v2
	v_lshlrev_b64 v[208:209], 11, v[2:3]
	v_lshl_add_u64 v[2:3], v[0:1], 0, v[208:209]
	v_lshl_add_u64 v[206:207], v[218:219], 0, s[92:93]
	s_mov_b64 s[14:15], 0x48000
	global_load_dwordx4 v[164:167], v[2:3], off
	global_load_dwordx4 v[160:163], v[2:3], off offset:256
	v_lshl_add_u64 v[2:3], v[0:1], 0, v[206:207]
	v_lshl_add_u64 v[204:205], v[218:219], 0, s[14:15]
	s_mov_b64 s[14:15], 0x50000
	global_load_dwordx4 v[28:31], v[2:3], off
	global_load_dwordx4 v[24:27], v[2:3], off offset:256
	v_lshl_add_u64 v[2:3], v[0:1], 0, v[204:205]
	v_lshl_add_u64 v[202:203], v[218:219], 0, s[14:15]
	v_lshl_add_u64 v[200:201], v[218:219], 0, s[2:3]
	global_load_dwordx4 v[20:23], v[2:3], off
	global_load_dwordx4 v[16:19], v[2:3], off offset:256
	v_lshl_add_u64 v[2:3], v[0:1], 0, v[202:203]
	v_lshl_add_u64 v[0:1], v[0:1], 0, v[200:201]
	global_load_dwordx4 v[12:15], v[2:3], off
	global_load_dwordx4 v[8:11], v[2:3], off offset:256
	global_load_dwordx4 v[4:7], v[0:1], off
	s_nop 0
	global_load_dwordx4 v[0:3], v[0:1], off offset:256
	s_brev_b32 s14, 60
	v_lshl_add_u64 v[218:219], s[64:65], 0, v[218:219]
	v_lshl_add_u64 v[216:217], v[218:219], 0, v[216:217]
	s_waitcnt vmcnt(0)
	v_lshlrev_b32_e32 v232, 16, v224
	v_and_b32_e32 v233, 0xffff0000, v224
	v_lshlrev_b32_e32 v224, 16, v225
	v_and_b32_e32 v225, 0xffff0000, v225
	v_pk_fma_f32 v[158:159], v[158:159], s[14:15], v[224:225] op_sel_hi:[1,0,1]
	v_pk_fma_f32 v[156:157], v[156:157], s[14:15], v[232:233] op_sel_hi:[1,0,1]
	v_lshlrev_b32_e32 v224, 16, v228
	v_and_b32_e32 v225, 0xffff0000, v228
	v_lshlrev_b32_e32 v234, 16, v226
	v_and_b32_e32 v235, 0xffff0000, v226
	v_lshlrev_b32_e32 v226, 16, v227
	v_and_b32_e32 v227, 0xffff0000, v227
	v_pk_fma_f32 v[148:149], v[148:149], s[14:15], v[224:225] op_sel_hi:[1,0,1]
	v_cvt_pk_bf16_f32 v224, v156, v157
	v_mul_f32_e32 v157, v157, v157
	v_pk_fma_f32 v[154:155], v[154:155], s[14:15], v[226:227] op_sel_hi:[1,0,1]
	v_pk_fma_f32 v[152:153], v[152:153], s[14:15], v[234:235] op_sel_hi:[1,0,1]
	v_lshlrev_b32_e32 v226, 16, v229
	v_and_b32_e32 v227, 0xffff0000, v229
	v_fmac_f32_e32 v157, v156, v156
	v_mul_f32_e32 v156, v159, v159
	v_pk_fma_f32 v[150:151], v[150:151], s[14:15], v[226:227] op_sel_hi:[1,0,1]
	v_cvt_pk_bf16_f32 v225, v158, v159
	v_cvt_pk_bf16_f32 v226, v152, v153
	v_fmac_f32_e32 v156, v158, v158
	v_mul_f32_e32 v153, v153, v153
	v_add_f32_e32 v156, v157, v156
	v_fmac_f32_e32 v153, v152, v152
	v_add_f32_e32 v152, v153, v156
	v_mul_f32_e32 v153, v155, v155
	v_fmac_f32_e32 v153, v154, v154
	v_lshlrev_b32_e32 v228, 16, v230
	v_and_b32_e32 v229, 0xffff0000, v230
	v_cvt_pk_bf16_f32 v227, v154, v155
	global_store_dwordx4 v[216:217], v[224:227], off
	v_add_f32_e32 v156, v153, v152
	v_cvt_pk_bf16_f32 v152, v148, v149
	v_mul_f32_e32 v149, v149, v149
	v_pk_fma_f32 v[144:145], v[144:145], s[14:15], v[228:229] op_sel_hi:[1,0,1]
	v_fmac_f32_e32 v149, v148, v148
	v_mul_f32_e32 v148, v151, v151
	v_lshlrev_b32_e32 v230, 16, v231
	v_and_b32_e32 v231, 0xffff0000, v231
	v_cvt_pk_bf16_f32 v153, v150, v151
	v_cvt_pk_bf16_f32 v154, v144, v145
	v_fmac_f32_e32 v148, v150, v150
	v_mul_f32_e32 v145, v145, v145
	v_pk_fma_f32 v[146:147], v[146:147], s[14:15], v[230:231] op_sel_hi:[1,0,1]
	v_add_f32_e32 v148, v149, v148
	v_fmac_f32_e32 v145, v144, v144
	v_add_f32_e32 v144, v145, v148
	v_mul_f32_e32 v145, v147, v147
	v_cvt_pk_bf16_f32 v155, v146, v147
	v_fmac_f32_e32 v145, v146, v146
	v_and_b32_e32 v146, 64, v243
	v_add_f32_e32 v144, v145, v144
	v_xor_b32_e32 v145, 16, v243
	v_add_u32_e32 v147, 64, v146
	v_cmp_lt_i32_e32 vcc, v145, v147
	v_add_f32_e32 v144, v156, v144
	global_store_dwordx4 v[216:217], v[152:155], off offset:256
	v_cndmask_b32_e32 v145, v243, v145, vcc
	v_lshlrev_b32_e32 v146, 2, v145
	v_mov_b32_e32 v145, v144
	s_nop 1
	v_permlane16_swap_b32_e32 v144, v145
	s_waitcnt lgkmcnt(0)
	v_add_f32_e32 v148, v144, v145
	v_xor_b32_e32 v144, 32, v243
	v_cmp_lt_i32_e32 vcc, v144, v147
	s_nop 1
	v_cndmask_b32_e32 v144, v243, v144, vcc
	v_lshlrev_b32_e32 v147, 2, v144
	v_mov_b32_e32 v149, v148
	s_nop 1
	v_permlane32_swap_b32_e32 v148, v149
	v_lshl_add_u64 v[144:145], v[214:215], 2, s[44:45]
	s_and_saveexec_b64 s[14:15], s[36:37]
	s_movk_i32 s85, 0xe00
	s_mov_b32 s84, 0x2aaaaaab
	s_mov_b64 s[82:83], 0x2c080
	s_mov_b64 s[80:81], 0x58080
	s_mov_b64 s[74:75], 0x84080
	s_cbranch_execz .LBB0_322
	s_waitcnt lgkmcnt(0)
	v_add_f32_e32 v148, v148, v149
	v_fma_f32 v148, v148, s18, 0.5
	v_cvt_u32_f32_e32 v148, v148
	global_atomic_add v[144:145], v148, off
.LBB0_322:
	s_or_b64 exec, exec, s[14:15]
	v_lshlrev_b32_e32 v148, 16, v180
	s_waitcnt lgkmcnt(0)
	v_and_b32_e32 v149, 0xffff0000, v180
	v_lshlrev_b32_e32 v150, 16, v181
	v_and_b32_e32 v151, 0xffff0000, v181
	v_lshlrev_b32_e32 v152, 16, v182
	v_and_b32_e32 v153, 0xffff0000, v182
	s_brev_b32 s14, 60
	v_pk_fma_f32 v[142:143], v[142:143], s[14:15], v[150:151] op_sel_hi:[1,0,1]
	v_pk_fma_f32 v[140:141], v[140:141], s[14:15], v[148:149] op_sel_hi:[1,0,1]
	v_pk_fma_f32 v[136:137], v[136:137], s[14:15], v[152:153] op_sel_hi:[1,0,1]
	v_lshlrev_b32_e32 v150, 16, v177
	v_and_b32_e32 v151, 0xffff0000, v177
	v_lshlrev_b32_e32 v152, 16, v178
	v_and_b32_e32 v153, 0xffff0000, v178
	v_lshlrev_b32_e32 v154, 16, v183
	v_and_b32_e32 v155, 0xffff0000, v183
	v_pk_fma_f32 v[134:135], v[134:135], s[14:15], v[150:151] op_sel_hi:[1,0,1]
	v_pk_fma_f32 v[150:151], v[128:129], s[14:15], v[152:153] op_sel_hi:[1,0,1]
	v_cvt_pk_bf16_f32 v128, v140, v141
	v_mul_f32_e32 v141, v141, v141
	v_pk_fma_f32 v[138:139], v[138:139], s[14:15], v[154:155] op_sel_hi:[1,0,1]
	v_lshlrev_b32_e32 v148, 16, v176
	v_and_b32_e32 v149, 0xffff0000, v176
	v_lshlrev_b32_e32 v154, 16, v179
	v_and_b32_e32 v155, 0xffff0000, v179
	v_fmac_f32_e32 v141, v140, v140
	v_mul_f32_e32 v140, v143, v143
	v_pk_fma_f32 v[132:133], v[132:133], s[14:15], v[148:149] op_sel_hi:[1,0,1]
	v_pk_fma_f32 v[148:149], v[130:131], s[14:15], v[154:155] op_sel_hi:[1,0,1]
	v_cvt_pk_bf16_f32 v129, v142, v143
	v_cvt_pk_bf16_f32 v130, v136, v137
	v_fmac_f32_e32 v140, v142, v142
	v_mul_f32_e32 v137, v137, v137
	v_add_f32_e32 v140, v141, v140
	v_fmac_f32_e32 v137, v136, v136
	v_add_f32_e32 v136, v137, v140
	v_mul_f32_e32 v137, v139, v139
	v_fmac_f32_e32 v137, v138, v138
	v_cvt_pk_bf16_f32 v131, v138, v139
	v_add_f32_e32 v136, v137, v136
	v_mul_f32_e32 v137, v133, v133
	v_mul_f32_e32 v138, v135, v135
	v_fmac_f32_e32 v137, v132, v132
	v_fmac_f32_e32 v138, v134, v134
	v_add_f32_e32 v137, v137, v138
	v_mul_f32_e32 v138, v151, v151
	v_fmac_f32_e32 v138, v150, v150
	v_add_f32_e32 v137, v138, v137
	v_mul_f32_e32 v138, v149, v149
	v_fmac_f32_e32 v138, v148, v148
	v_add_f32_e32 v137, v138, v137
	v_add_f32_e32 v138, v136, v137
	v_mov_b32_e32 v139, v138
	s_nop 1
	v_permlane16_swap_b32_e32 v138, v139
	v_lshl_add_u64 v[136:137], s[64:65], 0, v[212:213]
	v_lshl_add_u64 v[136:137], v[198:199], 1, v[136:137]
	global_store_dwordx4 v[136:137], v[128:131], off
	s_waitcnt lgkmcnt(0)
	s_nop 0
	v_add_f32_e32 v128, v138, v139
	v_mov_b32_e32 v129, v128
	s_nop 1
	v_permlane32_swap_b32_e32 v128, v129
	v_cvt_pk_bf16_f32 v130, v132, v133
	v_cvt_pk_bf16_f32 v131, v134, v135
	v_cvt_pk_bf16_f32 v132, v150, v151
	v_cvt_pk_bf16_f32 v133, v148, v149
	global_store_dwordx4 v[136:137], v[130:133], off offset:256
	s_and_saveexec_b64 s[14:15], s[36:37]
	s_cbranch_execz .LBB0_324
	s_waitcnt lgkmcnt(0)
	v_add_f32_e32 v128, v128, v129
	v_fma_f32 v128, v128, s18, 0.5
	v_cvt_u32_f32_e32 v128, v128
	global_atomic_add v[144:145], v128, off offset:64
.LBB0_324:
	s_or_b64 exec, exec, s[14:15]
	v_lshlrev_b32_e32 v128, 16, v172
	s_waitcnt lgkmcnt(0)
	v_and_b32_e32 v129, 0xffff0000, v172
	v_lshlrev_b32_e32 v130, 16, v173
	v_and_b32_e32 v131, 0xffff0000, v173
	v_lshlrev_b32_e32 v132, 16, v174
	v_and_b32_e32 v133, 0xffff0000, v174
	s_brev_b32 s14, 60
	v_pk_fma_f32 v[126:127], v[126:127], s[14:15], v[130:131] op_sel_hi:[1,0,1]
	v_pk_fma_f32 v[124:125], v[124:125], s[14:15], v[128:129] op_sel_hi:[1,0,1]
	v_pk_fma_f32 v[120:121], v[120:121], s[14:15], v[132:133] op_sel_hi:[1,0,1]
	v_lshlrev_b32_e32 v130, 16, v169
	v_and_b32_e32 v131, 0xffff0000, v169
	v_lshlrev_b32_e32 v132, 16, v170
	v_and_b32_e32 v133, 0xffff0000, v170
	v_lshlrev_b32_e32 v134, 16, v175
	v_and_b32_e32 v135, 0xffff0000, v175
	v_pk_fma_f32 v[118:119], v[118:119], s[14:15], v[130:131] op_sel_hi:[1,0,1]
	v_pk_fma_f32 v[130:131], v[112:113], s[14:15], v[132:133] op_sel_hi:[1,0,1]
	v_cvt_pk_bf16_f32 v112, v124, v125
	v_mul_f32_e32 v125, v125, v125
	v_pk_fma_f32 v[122:123], v[122:123], s[14:15], v[134:135] op_sel_hi:[1,0,1]
	v_lshlrev_b32_e32 v128, 16, v168
	v_and_b32_e32 v129, 0xffff0000, v168
	v_lshlrev_b32_e32 v134, 16, v171
	v_and_b32_e32 v135, 0xffff0000, v171
	v_fmac_f32_e32 v125, v124, v124
	v_mul_f32_e32 v124, v127, v127
	v_pk_fma_f32 v[116:117], v[116:117], s[14:15], v[128:129] op_sel_hi:[1,0,1]
	v_pk_fma_f32 v[128:129], v[114:115], s[14:15], v[134:135] op_sel_hi:[1,0,1]
	v_cvt_pk_bf16_f32 v113, v126, v127
	v_cvt_pk_bf16_f32 v114, v120, v121
	v_fmac_f32_e32 v124, v126, v126
	v_mul_f32_e32 v121, v121, v121
	v_add_f32_e32 v124, v125, v124
	v_fmac_f32_e32 v121, v120, v120
	v_add_f32_e32 v120, v121, v124
	v_mul_f32_e32 v121, v123, v123
	v_fmac_f32_e32 v121, v122, v122
	v_cvt_pk_bf16_f32 v115, v122, v123
	v_add_f32_e32 v120, v121, v120
	v_mul_f32_e32 v121, v117, v117
	v_mul_f32_e32 v122, v119, v119
	v_fmac_f32_e32 v121, v116, v116
	v_fmac_f32_e32 v122, v118, v118
	v_add_f32_e32 v121, v121, v122
	v_mul_f32_e32 v122, v131, v131
	v_fmac_f32_e32 v122, v130, v130
	v_add_f32_e32 v121, v122, v121
	v_mul_f32_e32 v122, v129, v129
	v_fmac_f32_e32 v122, v128, v128
	v_add_f32_e32 v121, v122, v121
	v_add_f32_e32 v122, v120, v121
	v_mov_b32_e32 v123, v122
	s_nop 1
	v_permlane16_swap_b32_e32 v122, v123
	v_lshl_add_u64 v[120:121], s[64:65], 0, v[210:211]
	v_lshl_add_u64 v[120:121], v[198:199], 1, v[120:121]
	global_store_dwordx4 v[120:121], v[112:115], off
	s_waitcnt lgkmcnt(0)
	s_nop 0
	v_add_f32_e32 v112, v122, v123
	v_mov_b32_e32 v113, v112
	s_nop 1
	v_permlane32_swap_b32_e32 v112, v113
	v_cvt_pk_bf16_f32 v114, v116, v117
	v_cvt_pk_bf16_f32 v115, v118, v119
	v_cvt_pk_bf16_f32 v116, v130, v131
	v_cvt_pk_bf16_f32 v117, v128, v129
	global_store_dwordx4 v[120:121], v[114:117], off offset:256
	s_and_saveexec_b64 s[14:15], s[36:37]
	s_mov_b32 s22, 0x2fffff
	s_cbranch_execz .LBB0_326
	s_waitcnt lgkmcnt(0)
	v_add_f32_e32 v112, v112, v113
	v_fma_f32 v112, v112, s18, 0.5
	v_cvt_u32_f32_e32 v112, v112
	global_atomic_add v[144:145], v112, off offset:128
.LBB0_326:
	s_or_b64 exec, exec, s[14:15]
	v_lshlrev_b32_e32 v112, 16, v164
	s_waitcnt lgkmcnt(0)
	v_and_b32_e32 v113, 0xffff0000, v164
	v_lshlrev_b32_e32 v114, 16, v165
	v_and_b32_e32 v115, 0xffff0000, v165
	v_lshlrev_b32_e32 v116, 16, v166
	v_and_b32_e32 v117, 0xffff0000, v166
	s_brev_b32 s14, 60
	v_pk_fma_f32 v[110:111], v[110:111], s[14:15], v[114:115] op_sel_hi:[1,0,1]
	v_pk_fma_f32 v[108:109], v[108:109], s[14:15], v[112:113] op_sel_hi:[1,0,1]
	v_pk_fma_f32 v[104:105], v[104:105], s[14:15], v[116:117] op_sel_hi:[1,0,1]
	v_lshlrev_b32_e32 v114, 16, v161
	v_and_b32_e32 v115, 0xffff0000, v161
	v_lshlrev_b32_e32 v116, 16, v162
	v_and_b32_e32 v117, 0xffff0000, v162
	v_lshlrev_b32_e32 v118, 16, v167
	v_and_b32_e32 v119, 0xffff0000, v167
	v_pk_fma_f32 v[102:103], v[102:103], s[14:15], v[114:115] op_sel_hi:[1,0,1]
	v_pk_fma_f32 v[114:115], v[96:97], s[14:15], v[116:117] op_sel_hi:[1,0,1]
	v_cvt_pk_bf16_f32 v96, v108, v109
	v_mul_f32_e32 v109, v109, v109
	v_pk_fma_f32 v[106:107], v[106:107], s[14:15], v[118:119] op_sel_hi:[1,0,1]
	v_lshlrev_b32_e32 v112, 16, v160
	v_and_b32_e32 v113, 0xffff0000, v160
	v_lshlrev_b32_e32 v118, 16, v163
	v_and_b32_e32 v119, 0xffff0000, v163
	v_fmac_f32_e32 v109, v108, v108
	v_mul_f32_e32 v108, v111, v111
	v_pk_fma_f32 v[100:101], v[100:101], s[14:15], v[112:113] op_sel_hi:[1,0,1]
	v_pk_fma_f32 v[112:113], v[98:99], s[14:15], v[118:119] op_sel_hi:[1,0,1]
	v_cvt_pk_bf16_f32 v97, v110, v111
	v_cvt_pk_bf16_f32 v98, v104, v105
	v_fmac_f32_e32 v108, v110, v110
	v_mul_f32_e32 v105, v105, v105
	v_add_f32_e32 v108, v109, v108
	v_fmac_f32_e32 v105, v104, v104
	v_add_f32_e32 v104, v105, v108
	v_mul_f32_e32 v105, v107, v107
	v_fmac_f32_e32 v105, v106, v106
	v_cvt_pk_bf16_f32 v99, v106, v107
	v_add_f32_e32 v104, v105, v104
	v_mul_f32_e32 v105, v101, v101
	v_mul_f32_e32 v106, v103, v103
	v_fmac_f32_e32 v105, v100, v100
	v_fmac_f32_e32 v106, v102, v102
	v_add_f32_e32 v105, v105, v106
	v_mul_f32_e32 v106, v115, v115
	v_fmac_f32_e32 v106, v114, v114
	v_add_f32_e32 v105, v106, v105
	v_mul_f32_e32 v106, v113, v113
	v_fmac_f32_e32 v106, v112, v112
	v_add_f32_e32 v105, v106, v105
	v_add_f32_e32 v106, v104, v105
	v_mov_b32_e32 v107, v106
	s_nop 1
	v_permlane16_swap_b32_e32 v106, v107
	v_lshl_add_u64 v[104:105], s[64:65], 0, v[208:209]
	v_lshl_add_u64 v[104:105], v[198:199], 1, v[104:105]
	global_store_dwordx4 v[104:105], v[96:99], off
	s_waitcnt lgkmcnt(0)
	s_nop 0
	v_add_f32_e32 v96, v106, v107
	v_mov_b32_e32 v97, v96
	s_nop 1
	v_permlane32_swap_b32_e32 v96, v97
	v_cvt_pk_bf16_f32 v98, v100, v101
	v_cvt_pk_bf16_f32 v99, v102, v103
	v_cvt_pk_bf16_f32 v100, v114, v115
	v_cvt_pk_bf16_f32 v101, v112, v113
	global_store_dwordx4 v[104:105], v[98:101], off offset:256
	s_and_saveexec_b64 s[14:15], s[36:37]
	s_cbranch_execz .LBB0_328
	s_waitcnt lgkmcnt(0)
	v_add_f32_e32 v96, v96, v97
	v_fma_f32 v96, v96, s18, 0.5
	v_cvt_u32_f32_e32 v96, v96
	global_atomic_add v[144:145], v96, off offset:192
.LBB0_328:
	s_or_b64 exec, exec, s[14:15]
	v_lshlrev_b32_e32 v96, 16, v28
	s_waitcnt lgkmcnt(0)
	v_and_b32_e32 v97, 0xffff0000, v28
	v_lshlrev_b32_e32 v28, 16, v29
	v_and_b32_e32 v29, 0xffff0000, v29
	v_lshlrev_b32_e32 v98, 16, v30
	v_and_b32_e32 v99, 0xffff0000, v30
	v_lshlrev_b32_e32 v30, 16, v31
	v_and_b32_e32 v31, 0xffff0000, v31
	s_brev_b32 s14, 60
	v_pk_fma_f32 v[28:29], v[94:95], s[14:15], v[28:29] op_sel_hi:[1,0,1]
	v_pk_fma_f32 v[92:93], v[92:93], s[14:15], v[96:97] op_sel_hi:[1,0,1]
	v_pk_fma_f32 v[30:31], v[90:91], s[14:15], v[30:31] op_sel_hi:[1,0,1]
	v_lshlrev_b32_e32 v90, 16, v24
	v_and_b32_e32 v91, 0xffff0000, v24
	v_lshlrev_b32_e32 v24, 16, v25
	v_and_b32_e32 v25, 0xffff0000, v25
	v_pk_fma_f32 v[86:87], v[86:87], s[14:15], v[24:25] op_sel_hi:[1,0,1]
	v_pk_fma_f32 v[84:85], v[84:85], s[14:15], v[90:91] op_sel_hi:[1,0,1]
	v_cvt_pk_bf16_f32 v24, v92, v93
	v_cvt_pk_bf16_f32 v25, v28, v29
	v_mul_f32_e32 v90, v93, v93
	v_mul_f32_e32 v29, v29, v29
	v_pk_fma_f32 v[88:89], v[88:89], s[14:15], v[98:99] op_sel_hi:[1,0,1]
	v_fmac_f32_e32 v90, v92, v92
	v_fmac_f32_e32 v29, v28, v28
	v_add_f32_e32 v28, v90, v29
	v_mul_f32_e32 v29, v89, v89
	v_fmac_f32_e32 v29, v88, v88
	v_add_f32_e32 v28, v29, v28
	v_mul_f32_e32 v29, v31, v31
	v_lshlrev_b32_e32 v94, 16, v26
	v_and_b32_e32 v95, 0xffff0000, v26
	v_lshlrev_b32_e32 v26, 16, v27
	v_and_b32_e32 v27, 0xffff0000, v27
	v_fmac_f32_e32 v29, v30, v30
	v_pk_fma_f32 v[82:83], v[82:83], s[14:15], v[26:27] op_sel_hi:[1,0,1]
	v_cvt_pk_bf16_f32 v26, v88, v89
	v_cvt_pk_bf16_f32 v27, v30, v31
	v_add_f32_e32 v28, v29, v28
	v_mul_f32_e32 v29, v85, v85
	v_mul_f32_e32 v30, v87, v87
	v_pk_fma_f32 v[80:81], v[80:81], s[14:15], v[94:95] op_sel_hi:[1,0,1]
	v_fmac_f32_e32 v29, v84, v84
	v_fmac_f32_e32 v30, v86, v86
	v_add_f32_e32 v29, v29, v30
	v_mul_f32_e32 v30, v81, v81
	v_fmac_f32_e32 v30, v80, v80
	v_add_f32_e32 v29, v30, v29
	v_mul_f32_e32 v30, v83, v83
	v_fmac_f32_e32 v30, v82, v82
	v_add_f32_e32 v29, v30, v29
	v_add_f32_e32 v88, v28, v29
	v_mov_b32_e32 v89, v88
	s_nop 1
	v_permlane16_swap_b32_e32 v88, v89
	v_lshl_add_u64 v[28:29], s[64:65], 0, v[206:207]
	v_lshl_add_u64 v[30:31], v[198:199], 1, v[28:29]
	global_store_dwordx4 v[30:31], v[24:27], off
	s_waitcnt lgkmcnt(0)
	s_nop 0
	v_add_f32_e32 v24, v88, v89
	v_mov_b32_e32 v25, v24
	s_nop 1
	v_permlane32_swap_b32_e32 v24, v25
	v_cvt_pk_bf16_f32 v26, v84, v85
	v_cvt_pk_bf16_f32 v27, v86, v87
	v_cvt_pk_bf16_f32 v28, v80, v81
	v_cvt_pk_bf16_f32 v29, v82, v83
	global_store_dwordx4 v[30:31], v[26:29], off offset:256
	s_and_saveexec_b64 s[14:15], s[36:37]
	s_cbranch_execz .LBB0_330
	s_waitcnt lgkmcnt(0)
	v_add_f32_e32 v24, v24, v25
	v_fma_f32 v24, v24, s18, 0.5
	v_cvt_u32_f32_e32 v24, v24
	global_atomic_add v[144:145], v24, off offset:512
.LBB0_330:
	s_or_b64 exec, exec, s[14:15]
	v_lshlrev_b32_e32 v24, 16, v20
	s_waitcnt lgkmcnt(0)
	v_and_b32_e32 v25, 0xffff0000, v20
	v_lshlrev_b32_e32 v20, 16, v21
	v_and_b32_e32 v21, 0xffff0000, v21
	s_brev_b32 s14, 60
	v_pk_fma_f32 v[20:21], v[78:79], s[14:15], v[20:21] op_sel_hi:[1,0,1]
	v_pk_fma_f32 v[24:25], v[76:77], s[14:15], v[24:25] op_sel_hi:[1,0,1]
	v_lshlrev_b32_e32 v28, 16, v16
	v_and_b32_e32 v29, 0xffff0000, v16
	v_lshlrev_b32_e32 v16, 16, v17
	v_and_b32_e32 v17, 0xffff0000, v17
	v_lshlrev_b32_e32 v26, 16, v22
	v_and_b32_e32 v27, 0xffff0000, v22
	v_pk_fma_f32 v[70:71], v[70:71], s[14:15], v[16:17] op_sel_hi:[1,0,1]
	v_cvt_pk_bf16_f32 v16, v24, v25
	v_cvt_pk_bf16_f32 v17, v20, v21
	v_mul_f32_e32 v25, v25, v25
	v_mul_f32_e32 v21, v21, v21
	v_pk_fma_f32 v[26:27], v[72:73], s[14:15], v[26:27] op_sel_hi:[1,0,1]
	v_fmac_f32_e32 v25, v24, v24
	v_fmac_f32_e32 v21, v20, v20
	v_lshlrev_b32_e32 v22, 16, v23
	v_and_b32_e32 v23, 0xffff0000, v23
	v_add_f32_e32 v20, v25, v21
	v_mul_f32_e32 v21, v27, v27
	v_pk_fma_f32 v[22:23], v[74:75], s[14:15], v[22:23] op_sel_hi:[1,0,1]
	v_fmac_f32_e32 v21, v26, v26
	v_add_f32_e32 v20, v21, v20
	v_mul_f32_e32 v21, v23, v23
	v_lshlrev_b32_e32 v30, 16, v18
	v_and_b32_e32 v31, 0xffff0000, v18
	v_lshlrev_b32_e32 v18, 16, v19
	v_and_b32_e32 v19, 0xffff0000, v19
	v_pk_fma_f32 v[28:29], v[68:69], s[14:15], v[28:29] op_sel_hi:[1,0,1]
	v_fmac_f32_e32 v21, v22, v22
	v_pk_fma_f32 v[66:67], v[66:67], s[14:15], v[18:19] op_sel_hi:[1,0,1]
	v_cvt_pk_bf16_f32 v18, v26, v27
	v_cvt_pk_bf16_f32 v19, v22, v23
	v_add_f32_e32 v20, v21, v20
	v_mul_f32_e32 v21, v29, v29
	v_mul_f32_e32 v22, v71, v71
	v_pk_fma_f32 v[30:31], v[64:65], s[14:15], v[30:31] op_sel_hi:[1,0,1]
	v_fmac_f32_e32 v21, v28, v28
	v_fmac_f32_e32 v22, v70, v70
	v_add_f32_e32 v21, v21, v22
	v_mul_f32_e32 v22, v31, v31
	v_fmac_f32_e32 v22, v30, v30
	v_add_f32_e32 v21, v22, v21
	v_mul_f32_e32 v22, v67, v67
	v_fmac_f32_e32 v22, v66, v66
	v_add_f32_e32 v21, v22, v21
	v_add_f32_e32 v24, v20, v21
	v_mov_b32_e32 v25, v24
	s_nop 1
	v_permlane16_swap_b32_e32 v24, v25
	v_lshl_add_u64 v[20:21], s[64:65], 0, v[204:205]
	v_lshl_add_u64 v[22:23], v[198:199], 1, v[20:21]
	global_store_dwordx4 v[22:23], v[16:19], off
	s_waitcnt lgkmcnt(0)
	s_nop 0
	v_add_f32_e32 v16, v24, v25
	v_mov_b32_e32 v17, v16
	s_nop 1
	v_permlane32_swap_b32_e32 v16, v17
	v_cvt_pk_bf16_f32 v18, v28, v29
	v_cvt_pk_bf16_f32 v19, v70, v71
	v_cvt_pk_bf16_f32 v20, v30, v31
	v_cvt_pk_bf16_f32 v21, v66, v67
	global_store_dwordx4 v[22:23], v[18:21], off offset:256
	s_and_saveexec_b64 s[14:15], s[36:37]
	s_cbranch_execz .LBB0_332
	s_waitcnt lgkmcnt(0)
	v_add_f32_e32 v16, v16, v17
	v_fma_f32 v16, v16, s18, 0.5
	v_cvt_u32_f32_e32 v16, v16
	global_atomic_add v[144:145], v16, off offset:576
.LBB0_332:
	s_or_b64 exec, exec, s[14:15]
	v_lshlrev_b32_e32 v16, 16, v12
	s_waitcnt lgkmcnt(0)
	v_and_b32_e32 v17, 0xffff0000, v12
	v_lshlrev_b32_e32 v12, 16, v13
	v_and_b32_e32 v13, 0xffff0000, v13
	s_brev_b32 s14, 60
	v_pk_fma_f32 v[12:13], v[62:63], s[14:15], v[12:13] op_sel_hi:[1,0,1]
	v_pk_fma_f32 v[16:17], v[60:61], s[14:15], v[16:17] op_sel_hi:[1,0,1]
	v_lshlrev_b32_e32 v20, 16, v8
	v_and_b32_e32 v21, 0xffff0000, v8
	v_lshlrev_b32_e32 v8, 16, v9
	v_and_b32_e32 v9, 0xffff0000, v9
	v_lshlrev_b32_e32 v18, 16, v14
	v_and_b32_e32 v19, 0xffff0000, v14
	v_pk_fma_f32 v[24:25], v[54:55], s[14:15], v[8:9] op_sel_hi:[1,0,1]
	v_cvt_pk_bf16_f32 v8, v16, v17
	v_cvt_pk_bf16_f32 v9, v12, v13
	v_mul_f32_e32 v17, v17, v17
	v_mul_f32_e32 v13, v13, v13
	v_pk_fma_f32 v[18:19], v[56:57], s[14:15], v[18:19] op_sel_hi:[1,0,1]
	v_fmac_f32_e32 v17, v16, v16
	v_fmac_f32_e32 v13, v12, v12
	v_lshlrev_b32_e32 v14, 16, v15
	v_and_b32_e32 v15, 0xffff0000, v15
	v_add_f32_e32 v12, v17, v13
	v_mul_f32_e32 v13, v19, v19
	v_pk_fma_f32 v[14:15], v[58:59], s[14:15], v[14:15] op_sel_hi:[1,0,1]
	v_fmac_f32_e32 v13, v18, v18
	v_add_f32_e32 v12, v13, v12
	v_mul_f32_e32 v13, v15, v15
	v_lshlrev_b32_e32 v22, 16, v10
	v_and_b32_e32 v23, 0xffff0000, v10
	v_lshlrev_b32_e32 v10, 16, v11
	v_and_b32_e32 v11, 0xffff0000, v11
	v_pk_fma_f32 v[20:21], v[52:53], s[14:15], v[20:21] op_sel_hi:[1,0,1]
	v_fmac_f32_e32 v13, v14, v14
	v_pk_fma_f32 v[26:27], v[50:51], s[14:15], v[10:11] op_sel_hi:[1,0,1]
	v_cvt_pk_bf16_f32 v10, v18, v19
	v_cvt_pk_bf16_f32 v11, v14, v15
	v_add_f32_e32 v12, v13, v12
	v_mul_f32_e32 v13, v21, v21
	v_mul_f32_e32 v14, v25, v25
	v_pk_fma_f32 v[22:23], v[48:49], s[14:15], v[22:23] op_sel_hi:[1,0,1]
	v_fmac_f32_e32 v13, v20, v20
	v_fmac_f32_e32 v14, v24, v24
	v_add_f32_e32 v13, v13, v14
	v_mul_f32_e32 v14, v23, v23
	v_fmac_f32_e32 v14, v22, v22
	v_add_f32_e32 v13, v14, v13
	v_mul_f32_e32 v14, v27, v27
	v_fmac_f32_e32 v14, v26, v26
	v_add_f32_e32 v13, v14, v13
	v_add_f32_e32 v16, v12, v13
	v_mov_b32_e32 v17, v16
	s_nop 1
	v_permlane16_swap_b32_e32 v16, v17
	v_lshl_add_u64 v[12:13], s[64:65], 0, v[202:203]
	v_lshl_add_u64 v[14:15], v[198:199], 1, v[12:13]
	global_store_dwordx4 v[14:15], v[8:11], off
	s_waitcnt lgkmcnt(0)
	s_nop 0
	v_add_f32_e32 v8, v16, v17
	v_mov_b32_e32 v9, v8
	s_nop 1
	v_permlane32_swap_b32_e32 v8, v9
	v_cvt_pk_bf16_f32 v10, v20, v21
	v_cvt_pk_bf16_f32 v11, v24, v25
	v_cvt_pk_bf16_f32 v12, v22, v23
	v_cvt_pk_bf16_f32 v13, v26, v27
	global_store_dwordx4 v[14:15], v[10:13], off offset:256
	s_and_saveexec_b64 s[14:15], s[36:37]
	s_cbranch_execz .LBB0_334
	s_waitcnt lgkmcnt(0)
	v_add_f32_e32 v8, v8, v9
	v_fma_f32 v8, v8, s18, 0.5
	v_cvt_u32_f32_e32 v8, v8
	global_atomic_add v[144:145], v8, off offset:640
.LBB0_334:
	s_or_b64 exec, exec, s[14:15]
	v_lshlrev_b32_e32 v8, 16, v4
	s_waitcnt lgkmcnt(0)
	v_and_b32_e32 v9, 0xffff0000, v4
	v_lshlrev_b32_e32 v4, 16, v5
	v_and_b32_e32 v5, 0xffff0000, v5
	s_brev_b32 s14, 60
	v_pk_fma_f32 v[4:5], v[46:47], s[14:15], v[4:5] op_sel_hi:[1,0,1]
	v_pk_fma_f32 v[8:9], v[44:45], s[14:15], v[8:9] op_sel_hi:[1,0,1]
	v_lshlrev_b32_e32 v12, 16, v0
	v_and_b32_e32 v13, 0xffff0000, v0
	v_lshlrev_b32_e32 v0, 16, v1
	v_and_b32_e32 v1, 0xffff0000, v1
	v_lshlrev_b32_e32 v10, 16, v6
	v_and_b32_e32 v11, 0xffff0000, v6
	v_pk_fma_f32 v[16:17], v[38:39], s[14:15], v[0:1] op_sel_hi:[1,0,1]
	v_cvt_pk_bf16_f32 v0, v8, v9
	v_cvt_pk_bf16_f32 v1, v4, v5
	v_mul_f32_e32 v9, v9, v9
	v_mul_f32_e32 v5, v5, v5
	v_pk_fma_f32 v[10:11], v[40:41], s[14:15], v[10:11] op_sel_hi:[1,0,1]
	v_fmac_f32_e32 v9, v8, v8
	v_fmac_f32_e32 v5, v4, v4
	v_lshlrev_b32_e32 v6, 16, v7
	v_and_b32_e32 v7, 0xffff0000, v7
	v_add_f32_e32 v4, v9, v5
	v_mul_f32_e32 v5, v11, v11
	v_pk_fma_f32 v[6:7], v[42:43], s[14:15], v[6:7] op_sel_hi:[1,0,1]
	v_fmac_f32_e32 v5, v10, v10
	v_add_f32_e32 v4, v5, v4
	v_mul_f32_e32 v5, v7, v7
	v_lshlrev_b32_e32 v14, 16, v2
	v_and_b32_e32 v15, 0xffff0000, v2
	v_lshlrev_b32_e32 v2, 16, v3
	v_and_b32_e32 v3, 0xffff0000, v3
	v_pk_fma_f32 v[12:13], v[36:37], s[14:15], v[12:13] op_sel_hi:[1,0,1]
	v_fmac_f32_e32 v5, v6, v6
	v_pk_fma_f32 v[18:19], v[34:35], s[14:15], v[2:3] op_sel_hi:[1,0,1]
	v_cvt_pk_bf16_f32 v2, v10, v11
	v_cvt_pk_bf16_f32 v3, v6, v7
	v_add_f32_e32 v4, v5, v4
	v_mul_f32_e32 v5, v13, v13
	v_mul_f32_e32 v6, v17, v17
	v_pk_fma_f32 v[14:15], v[32:33], s[14:15], v[14:15] op_sel_hi:[1,0,1]
	v_fmac_f32_e32 v5, v12, v12
	v_fmac_f32_e32 v6, v16, v16
	v_add_f32_e32 v5, v5, v6
	v_mul_f32_e32 v6, v15, v15
	v_fmac_f32_e32 v6, v14, v14
	v_add_f32_e32 v5, v6, v5
	v_mul_f32_e32 v6, v19, v19
	v_fmac_f32_e32 v6, v18, v18
	v_add_f32_e32 v5, v6, v5
	v_add_f32_e32 v8, v4, v5
	v_mov_b32_e32 v9, v8
	s_nop 1
	v_permlane16_swap_b32_e32 v8, v9
	v_lshl_add_u64 v[4:5], s[64:65], 0, v[200:201]
	v_lshl_add_u64 v[6:7], v[198:199], 1, v[4:5]
	global_store_dwordx4 v[6:7], v[0:3], off
	s_waitcnt lgkmcnt(0)
	s_nop 0
	v_add_f32_e32 v0, v8, v9
	v_mov_b32_e32 v1, v0
	s_nop 1
	v_permlane32_swap_b32_e32 v0, v1
	v_cvt_pk_bf16_f32 v2, v12, v13
	v_cvt_pk_bf16_f32 v3, v16, v17
	v_cvt_pk_bf16_f32 v4, v14, v15
	v_cvt_pk_bf16_f32 v5, v18, v19
	global_store_dwordx4 v[6:7], v[2:5], off offset:256
	s_and_saveexec_b64 s[14:15], s[36:37]
	s_cbranch_execz .LBB0_336
	s_waitcnt lgkmcnt(0)
	v_add_f32_e32 v0, v0, v1
	v_fma_f32 v0, v0, s18, 0.5
	v_cvt_u32_f32_e32 v0, v0
	global_atomic_add v[144:145], v0, off offset:704

.LBB0_365:
	v_lshl_add_u32 v202, s85, 8, v222
	v_ashrrev_i32_e32 v203, 31, v202
	v_lshl_or_b32 v200, s45, 8, v224
	v_lshlrev_b64 v[208:209], 11, v[202:203]
	v_ashrrev_i32_e32 v201, 31, v200
	s_andn2_b64 vcc, exec, s[10:11]
	v_or_b32_e32 v176, 16, v202
	v_or_b32_e32 v212, 32, v202
	v_or_b32_e32 v210, 48, v202
	v_lshl_add_u64 v[206:207], s[64:65], 0, v[208:209]
	s_mov_b32 s18, 0x44800000
	s_cbranch_vccnz .LBB0_383
	v_lshl_add_u64 v[178:179], v[200:201], 2, s[74:75]
	v_lshlrev_b64 v[128:129], 12, v[202:203]
	v_lshl_add_u64 v[128:129], v[178:179], 0, v[128:129]
	global_load_dwordx4 v[180:183], v[128:129], off offset:16
	global_load_dwordx4 v[214:217], v[128:129], off
	global_load_dwordx4 v[218:221], v[128:129], off offset:528
	global_load_dwordx4 v[226:229], v[128:129], off offset:512
	v_ashrrev_i32_e32 v177, 31, v176
	v_lshlrev_b64 v[128:129], 12, v[176:177]
	v_lshl_add_u64 v[128:129], v[178:179], 0, v[128:129]
	v_ashrrev_i32_e32 v213, 31, v212
	global_load_dwordx4 v[168:171], v[128:129], off offset:16
	global_load_dwordx4 v[172:175], v[128:129], off
	global_load_dwordx4 v[160:163], v[128:129], off offset:528
	global_load_dwordx4 v[164:167], v[128:129], off offset:512
	v_lshlrev_b64 v[128:129], 12, v[212:213]
	v_lshl_add_u64 v[128:129], v[178:179], 0, v[128:129]
	v_ashrrev_i32_e32 v211, 31, v210
	global_load_dwordx4 v[152:155], v[128:129], off offset:16
	global_load_dwordx4 v[156:159], v[128:129], off
	global_load_dwordx4 v[144:147], v[128:129], off offset:528
	global_load_dwordx4 v[148:151], v[128:129], off offset:512
	v_lshlrev_b64 v[128:129], 12, v[210:211]
	v_lshl_add_u64 v[132:133], v[178:179], 0, v[128:129]
	global_load_dwordx4 v[136:139], v[132:133], off offset:16
	global_load_dwordx4 v[140:143], v[132:133], off
	global_load_dwordx4 v[128:131], v[132:133], off offset:528
	s_nop 0
	global_load_dwordx4 v[132:135], v[132:133], off offset:512
	s_waitcnt vmcnt(0)
	v_pk_fma_f32 v[204:205], s[48:49], v[122:123], v[182:183]
	v_pk_fma_f32 v[186:187], s[48:49], v[126:127], v[216:217]
	v_pk_fma_f32 v[188:189], s[42:43], v[124:125], v[214:215]
	v_pk_fma_f32 v[214:215], s[42:43], v[120:121], v[180:181]
	v_pk_fma_f32 v[216:217], s[48:49], v[118:119], v[228:229]
	v_cvt_pk_bf16_f32 v180, v188, v189
	v_cvt_pk_bf16_f32 v181, v186, v187
	v_lshl_add_u64 v[228:229], v[200:201], 1, v[206:207]
	v_cvt_pk_bf16_f32 v182, v214, v215
	v_cvt_pk_bf16_f32 v183, v204, v205
	global_store_dwordx4 v[228:229], v[180:183], off
	v_pk_fma_f32 v[226:227], s[42:43], v[116:117], v[226:227]
	v_pk_fma_f32 v[220:221], s[48:49], v[114:115], v[220:221]
	v_mul_f32_e32 v180, v189, v189
	v_mul_f32_e32 v181, v187, v187
	v_fmac_f32_e32 v180, v188, v188
	v_fmac_f32_e32 v181, v186, v186
	v_add_f32_e32 v180, v180, v181
	v_mul_f32_e32 v181, v215, v215
	v_fmac_f32_e32 v181, v214, v214
	v_add_f32_e32 v180, v181, v180
	v_mul_f32_e32 v181, v205, v205
	v_fmac_f32_e32 v181, v204, v204
	v_add_f32_e32 v186, v181, v180
	v_cvt_pk_bf16_f32 v180, v226, v227
	v_cvt_pk_bf16_f32 v181, v216, v217
	v_pk_fma_f32 v[218:219], s[42:43], v[112:113], v[218:219]
	s_nop 0
	v_cvt_pk_bf16_f32 v182, v218, v219
	v_cvt_pk_bf16_f32 v183, v220, v221
	global_store_dwordx4 v[228:229], v[180:183], off offset:256
	s_nop 1
	v_mul_f32_e32 v180, v227, v227
	v_mul_f32_e32 v181, v217, v217
	v_fmac_f32_e32 v180, v226, v226
	v_fmac_f32_e32 v181, v216, v216
	v_add_f32_e32 v180, v180, v181
	v_mul_f32_e32 v181, v219, v219
	v_fmac_f32_e32 v181, v218, v218
	v_add_f32_e32 v180, v181, v180
	v_mul_f32_e32 v181, v221, v221
	v_fmac_f32_e32 v181, v220, v220
	v_and_b32_e32 v182, 64, v243
	v_add_f32_e32 v180, v181, v180
	v_xor_b32_e32 v181, 16, v243
	v_add_u32_e32 v182, 64, v182
	v_cmp_lt_i32_e32 vcc, v181, v182
	v_add_f32_e32 v180, v186, v180
	s_nop 0
	v_cndmask_b32_e32 v181, v243, v181, vcc
	v_lshlrev_b32_e32 v214, 2, v181
	v_mov_b32_e32 v181, v180
	s_nop 1
	v_permlane16_swap_b32_e32 v180, v181
	s_waitcnt lgkmcnt(0)
	v_add_f32_e32 v180, v180, v181
	v_xor_b32_e32 v181, 32, v243
	v_cmp_lt_i32_e32 vcc, v181, v182
	s_nop 1
	v_cndmask_b32_e32 v181, v243, v181, vcc
	v_lshlrev_b32_e32 v215, 2, v181
	v_mov_b32_e32 v181, v180
	s_nop 1
	v_permlane32_swap_b32_e32 v180, v181
	s_and_saveexec_b64 s[14:15], s[8:9]
	s_cbranch_execz .LBB0_368
	s_waitcnt lgkmcnt(0)
	v_add_f32_e32 v180, v180, v181
	v_fma_f32 v180, v180, s18, 0.5
	v_cvt_u32_f32_e32 v182, v180
	v_lshl_add_u64 v[180:181], v[202:203], 2, s[36:37]
	global_atomic_add v[180:181], v182, off
.LBB0_368:
	s_or_b64 exec, exec, s[14:15]
	v_pk_fma_f32 v[172:173], s[42:43], v[108:109], v[172:173]
	v_pk_fma_f32 v[174:175], s[48:49], v[110:111], v[174:175]
	v_pk_fma_f32 v[182:183], s[42:43], v[96:97], v[160:161]
	v_cvt_pk_bf16_f32 v160, v172, v173
	v_mul_f32_e32 v173, v173, v173
	v_pk_fma_f32 v[168:169], s[42:43], v[104:105], v[168:169]
	v_fmac_f32_e32 v173, v172, v172
	v_mul_f32_e32 v172, v175, v175
	s_waitcnt lgkmcnt(0)
	v_pk_fma_f32 v[180:181], s[48:49], v[98:99], v[162:163]
	v_cvt_pk_bf16_f32 v161, v174, v175
	v_cvt_pk_bf16_f32 v162, v168, v169
	v_fmac_f32_e32 v172, v174, v174
	v_mul_f32_e32 v169, v169, v169
	v_pk_fma_f32 v[170:171], s[48:49], v[106:107], v[170:171]
	v_add_f32_e32 v172, v173, v172
	v_fmac_f32_e32 v169, v168, v168
	v_add_f32_e32 v168, v169, v172
	v_mul_f32_e32 v169, v171, v171
	v_pk_fma_f32 v[166:167], s[48:49], v[102:103], v[166:167]
	v_pk_fma_f32 v[164:165], s[42:43], v[100:101], v[164:165]
	v_fmac_f32_e32 v169, v170, v170
	v_cvt_pk_bf16_f32 v163, v170, v171
	v_add_f32_e32 v168, v169, v168
	v_mul_f32_e32 v169, v165, v165
	v_mul_f32_e32 v170, v167, v167
	v_fmac_f32_e32 v169, v164, v164
	v_fmac_f32_e32 v170, v166, v166
	v_add_f32_e32 v169, v169, v170
	v_mul_f32_e32 v170, v183, v183
	v_fmac_f32_e32 v170, v182, v182
	v_add_f32_e32 v169, v170, v169
	v_mul_f32_e32 v170, v181, v181
	v_fmac_f32_e32 v170, v180, v180
	v_add_f32_e32 v169, v170, v169
	v_add_f32_e32 v170, v168, v169
	v_mov_b32_e32 v171, v170
	s_nop 1
	v_permlane16_swap_b32_e32 v170, v171
	v_lshlrev_b64 v[186:187], 11, v[176:177]
	v_lshl_add_u64 v[168:169], s[64:65], 0, v[186:187]
	v_lshl_add_u64 v[168:169], v[200:201], 1, v[168:169]
	global_store_dwordx4 v[168:169], v[160:163], off
	s_waitcnt lgkmcnt(0)
	s_nop 0
	v_add_f32_e32 v160, v170, v171
	v_mov_b32_e32 v161, v160
	s_nop 1
	v_permlane32_swap_b32_e32 v160, v161
	v_cvt_pk_bf16_f32 v162, v164, v165
	v_cvt_pk_bf16_f32 v163, v166, v167
	v_cvt_pk_bf16_f32 v164, v182, v183
	v_cvt_pk_bf16_f32 v165, v180, v181
	global_store_dwordx4 v[168:169], v[162:165], off offset:256
	s_and_saveexec_b64 s[14:15], s[8:9]
	s_cbranch_execz .LBB0_370
	s_waitcnt lgkmcnt(0)
	v_add_f32_e32 v160, v160, v161
	v_fma_f32 v160, v160, s18, 0.5
	v_cvt_u32_f32_e32 v162, v160
	v_lshl_add_u64 v[160:161], v[202:203], 2, s[36:37]
	global_atomic_add v[160:161], v162, off offset:64
.LBB0_370:
	s_or_b64 exec, exec, s[14:15]
	v_pk_fma_f32 v[156:157], s[42:43], v[92:93], v[156:157]
	v_pk_fma_f32 v[158:159], s[48:49], v[94:95], v[158:159]
	v_pk_fma_f32 v[162:163], s[42:43], v[80:81], v[144:145]
	v_cvt_pk_bf16_f32 v144, v156, v157
	v_mul_f32_e32 v157, v157, v157
	v_pk_fma_f32 v[152:153], s[42:43], v[88:89], v[152:153]
	v_fmac_f32_e32 v157, v156, v156
	v_mul_f32_e32 v156, v159, v159
	s_waitcnt lgkmcnt(0)
	v_pk_fma_f32 v[160:161], s[48:49], v[82:83], v[146:147]
	v_cvt_pk_bf16_f32 v145, v158, v159
	v_cvt_pk_bf16_f32 v146, v152, v153
	v_fmac_f32_e32 v156, v158, v158
	v_mul_f32_e32 v153, v153, v153
	v_pk_fma_f32 v[154:155], s[48:49], v[90:91], v[154:155]
	v_add_f32_e32 v156, v157, v156
	v_fmac_f32_e32 v153, v152, v152
	v_add_f32_e32 v152, v153, v156
	v_mul_f32_e32 v153, v155, v155
	v_pk_fma_f32 v[150:151], s[48:49], v[86:87], v[150:151]
	v_pk_fma_f32 v[148:149], s[42:43], v[84:85], v[148:149]
	v_fmac_f32_e32 v153, v154, v154
	v_cvt_pk_bf16_f32 v147, v154, v155
	v_add_f32_e32 v152, v153, v152
	v_mul_f32_e32 v153, v149, v149
	v_mul_f32_e32 v154, v151, v151
	v_fmac_f32_e32 v153, v148, v148
	v_fmac_f32_e32 v154, v150, v150
	v_add_f32_e32 v153, v153, v154
	v_mul_f32_e32 v154, v163, v163
	v_fmac_f32_e32 v154, v162, v162
	v_add_f32_e32 v153, v154, v153
	v_mul_f32_e32 v154, v161, v161
	v_fmac_f32_e32 v154, v160, v160
	v_add_f32_e32 v153, v154, v153
	v_add_f32_e32 v154, v152, v153
	v_mov_b32_e32 v155, v154
	s_nop 1
	v_permlane16_swap_b32_e32 v154, v155
	v_lshlrev_b64 v[164:165], 11, v[212:213]
	v_lshl_add_u64 v[152:153], s[64:65], 0, v[164:165]
	v_lshl_add_u64 v[152:153], v[200:201], 1, v[152:153]
	global_store_dwordx4 v[152:153], v[144:147], off
	s_waitcnt lgkmcnt(0)
	s_nop 0
	v_add_f32_e32 v144, v154, v155
	v_mov_b32_e32 v145, v144
	s_nop 1
	v_permlane32_swap_b32_e32 v144, v145
	v_cvt_pk_bf16_f32 v146, v148, v149
	v_cvt_pk_bf16_f32 v147, v150, v151
	v_cvt_pk_bf16_f32 v148, v162, v163
	v_cvt_pk_bf16_f32 v149, v160, v161
	global_store_dwordx4 v[152:153], v[146:149], off offset:256
	s_and_saveexec_b64 s[14:15], s[8:9]
	s_cbranch_execz .LBB0_372
	s_waitcnt lgkmcnt(0)
	v_add_f32_e32 v144, v144, v145
	v_fma_f32 v144, v144, s18, 0.5
	v_cvt_u32_f32_e32 v146, v144
	v_lshl_add_u64 v[144:145], v[202:203], 2, s[36:37]
	global_atomic_add v[144:145], v146, off offset:128
.LBB0_372:
	s_or_b64 exec, exec, s[14:15]
	v_pk_fma_f32 v[140:141], s[42:43], v[76:77], v[140:141]
	v_pk_fma_f32 v[142:143], s[48:49], v[78:79], v[142:143]
	v_pk_fma_f32 v[146:147], s[42:43], v[64:65], v[128:129]
	v_cvt_pk_bf16_f32 v128, v140, v141
	v_mul_f32_e32 v141, v141, v141
	v_pk_fma_f32 v[136:137], s[42:43], v[72:73], v[136:137]
	v_fmac_f32_e32 v141, v140, v140
	v_mul_f32_e32 v140, v143, v143
	s_waitcnt lgkmcnt(0)
	v_pk_fma_f32 v[144:145], s[48:49], v[66:67], v[130:131]
	v_cvt_pk_bf16_f32 v129, v142, v143
	v_cvt_pk_bf16_f32 v130, v136, v137
	v_fmac_f32_e32 v140, v142, v142
	v_mul_f32_e32 v137, v137, v137
	v_pk_fma_f32 v[138:139], s[48:49], v[74:75], v[138:139]
	v_add_f32_e32 v140, v141, v140
	v_fmac_f32_e32 v137, v136, v136
	v_add_f32_e32 v136, v137, v140
	v_mul_f32_e32 v137, v139, v139
	v_pk_fma_f32 v[134:135], s[48:49], v[70:71], v[134:135]
	v_pk_fma_f32 v[132:133], s[42:43], v[68:69], v[132:133]
	v_fmac_f32_e32 v137, v138, v138
	v_cvt_pk_bf16_f32 v131, v138, v139
	v_add_f32_e32 v136, v137, v136
	v_mul_f32_e32 v137, v133, v133
	v_mul_f32_e32 v138, v135, v135
	v_fmac_f32_e32 v137, v132, v132
	v_fmac_f32_e32 v138, v134, v134
	v_add_f32_e32 v137, v137, v138
	v_mul_f32_e32 v138, v147, v147
	v_fmac_f32_e32 v138, v146, v146
	v_add_f32_e32 v137, v138, v137
	v_mul_f32_e32 v138, v145, v145
	v_fmac_f32_e32 v138, v144, v144
	v_add_f32_e32 v137, v138, v137
	v_add_f32_e32 v138, v136, v137
	v_mov_b32_e32 v139, v138
	s_nop 1
	v_permlane16_swap_b32_e32 v138, v139
	v_lshlrev_b64 v[148:149], 11, v[210:211]
	v_lshl_add_u64 v[136:137], s[64:65], 0, v[148:149]
	v_lshl_add_u64 v[136:137], v[200:201], 1, v[136:137]
	global_store_dwordx4 v[136:137], v[128:131], off
	s_waitcnt lgkmcnt(0)
	s_nop 0
	v_add_f32_e32 v128, v138, v139
	v_mov_b32_e32 v129, v128
	s_nop 1
	v_permlane32_swap_b32_e32 v128, v129
	v_cvt_pk_bf16_f32 v130, v132, v133
	v_cvt_pk_bf16_f32 v131, v134, v135
	v_cvt_pk_bf16_f32 v132, v146, v147
	v_cvt_pk_bf16_f32 v133, v144, v145
	global_store_dwordx4 v[136:137], v[130:133], off offset:256
	s_and_saveexec_b64 s[14:15], s[8:9]
	s_cbranch_execz .LBB0_374
	s_waitcnt lgkmcnt(0)
	v_add_f32_e32 v128, v128, v129
	v_fma_f32 v128, v128, s18, 0.5
	v_cvt_u32_f32_e32 v130, v128
	v_lshl_add_u64 v[128:129], v[202:203], 2, s[36:37]
	global_atomic_add v[128:129], v130, off offset:192
.LBB0_374:
	s_or_b64 exec, exec, s[14:15]
	v_add_u32_e32 v186, 0x80, v202
	v_ashrrev_i32_e32 v187, 31, v186
	s_waitcnt lgkmcnt(0)
	v_lshlrev_b64 v[128:129], 12, v[186:187]
	v_lshl_add_u64 v[128:129], v[178:179], 0, v[128:129]
	global_load_dwordx4 v[216:219], v[128:129], off
	global_load_dwordx4 v[226:229], v[128:129], off offset:16
	global_load_dwordx4 v[230:233], v[128:129], off offset:512
	global_load_dwordx4 v[234:237], v[128:129], off offset:528
	v_add_u32_e32 v182, 0x90, v202
	v_add_u32_e32 v180, 0xa0, v202
	v_add_u32_e32 v204, 0xb0, v202
	v_ashrrev_i32_e32 v183, 31, v182
	v_ashrrev_i32_e32 v181, 31, v180
	v_ashrrev_i32_e32 v205, 31, v204
	v_lshlrev_b64 v[128:129], 12, v[182:183]
	v_lshlrev_b64 v[130:131], 12, v[180:181]
	v_lshlrev_b64 v[132:133], 12, v[204:205]
	v_lshl_add_u64 v[128:129], v[178:179], 0, v[128:129]
	v_lshl_add_u64 v[130:131], v[178:179], 0, v[130:131]
	v_lshl_add_u64 v[132:133], v[178:179], 0, v[132:133]
	global_load_dwordx4 v[168:171], v[128:129], off offset:16
	global_load_dwordx4 v[172:175], v[128:129], off
	global_load_dwordx4 v[160:163], v[128:129], off offset:528
	global_load_dwordx4 v[164:167], v[128:129], off offset:512
	global_load_dwordx4 v[152:155], v[130:131], off offset:16
	global_load_dwordx4 v[156:159], v[130:131], off
	global_load_dwordx4 v[144:147], v[130:131], off offset:528
	global_load_dwordx4 v[148:151], v[130:131], off offset:512
	global_load_dwordx4 v[136:139], v[132:133], off offset:16
	global_load_dwordx4 v[140:143], v[132:133], off
	s_nop 0
	global_load_dwordx4 v[128:131], v[132:133], off offset:528
	s_nop 0
	global_load_dwordx4 v[132:135], v[132:133], off offset:512
	v_lshlrev_b64 v[178:179], 11, v[186:187]
	v_lshl_add_u64 v[178:179], s[64:65], 0, v[178:179]
	s_waitcnt vmcnt(15)
	v_pk_fma_f32 v[186:187], s[48:49], v[62:63], v[218:219]
	v_pk_fma_f32 v[188:189], s[42:43], v[60:61], v[216:217]
	s_waitcnt vmcnt(14)
	v_pk_fma_f32 v[220:221], s[48:49], v[58:59], v[228:229]
	s_waitcnt vmcnt(13)
	v_pk_fma_f32 v[228:229], s[48:49], v[54:55], v[232:233]
	v_pk_fma_f32 v[230:231], s[42:43], v[52:53], v[230:231]
	v_pk_fma_f32 v[226:227], s[42:43], v[56:57], v[226:227]
	s_waitcnt vmcnt(12)
	v_pk_fma_f32 v[234:235], s[42:43], v[48:49], v[234:235]
	v_cvt_pk_bf16_f32 v216, v188, v189
	v_cvt_pk_bf16_f32 v217, v186, v187
	v_cvt_pk_bf16_f32 v218, v226, v227
	v_cvt_pk_bf16_f32 v219, v220, v221
	v_mul_f32_e32 v177, v189, v189
	v_mul_f32_e32 v187, v187, v187
	v_mul_f32_e32 v211, v221, v221
	v_mul_f32_e32 v213, v231, v231
	v_mul_f32_e32 v221, v229, v229
	v_pk_fma_f32 v[232:233], s[48:49], v[50:51], v[236:237]
	v_mul_f32_e32 v189, v227, v227
	v_mul_f32_e32 v227, v235, v235
	v_fmac_f32_e32 v177, v188, v188
	v_fmac_f32_e32 v187, v186, v186
	v_fmac_f32_e32 v213, v230, v230
	v_fmac_f32_e32 v221, v228, v228
	v_mul_f32_e32 v236, v233, v233
	v_fmac_f32_e32 v189, v226, v226
	v_fmac_f32_e32 v227, v234, v234
	v_add_f32_e32 v177, v177, v187
	v_add_f32_e32 v186, v213, v221
	v_fmac_f32_e32 v211, v220, v220
	v_fmac_f32_e32 v236, v232, v232
	v_add_f32_e32 v177, v189, v177
	v_add_f32_e32 v186, v227, v186
	v_add_f32_e32 v177, v211, v177
	v_add_f32_e32 v186, v236, v186
	v_add_f32_e32 v177, v177, v186
	v_mov_b32_e32 v188, v177
	s_nop 1
	v_permlane16_swap_b32_e32 v177, v188
	v_lshl_add_u64 v[186:187], v[200:201], 1, v[178:179]
	global_store_dwordx4 v[186:187], v[216:219], off
	s_waitcnt lgkmcnt(0)
	v_add_f32_e32 v177, v177, v188
	v_mov_b32_e32 v178, v177
	s_nop 1
	v_permlane32_swap_b32_e32 v177, v178
	v_cvt_pk_bf16_f32 v216, v230, v231
	v_cvt_pk_bf16_f32 v217, v228, v229
	v_cvt_pk_bf16_f32 v218, v234, v235
	v_cvt_pk_bf16_f32 v219, v232, v233
	global_store_dwordx4 v[186:187], v[216:219], off offset:256
	s_and_saveexec_b64 s[14:15], s[8:9]
	s_cbranch_execz .LBB0_376
	s_waitcnt lgkmcnt(0)
	v_add_f32_e32 v177, v177, v178
	v_fma_f32 v177, v177, s18, 0.5
	v_cvt_u32_f32_e32 v177, v177
	v_lshl_add_u64 v[178:179], v[202:203], 2, s[36:37]
	global_atomic_add v[178:179], v177, off offset:512
.LBB0_376:
	s_or_b64 exec, exec, s[14:15]
	s_waitcnt vmcnt(12)
	v_pk_fma_f32 v[172:173], s[42:43], v[44:45], v[172:173]
	v_pk_fma_f32 v[174:175], s[48:49], v[46:47], v[174:175]
	s_waitcnt vmcnt(11)
	v_pk_fma_f32 v[186:187], s[42:43], v[32:33], v[160:161]
	v_cvt_pk_bf16_f32 v160, v172, v173
	v_mul_f32_e32 v173, v173, v173
	v_pk_fma_f32 v[168:169], s[42:43], v[40:41], v[168:169]
	v_fmac_f32_e32 v173, v172, v172
	v_mul_f32_e32 v172, v175, v175
	s_waitcnt lgkmcnt(0)
	v_pk_fma_f32 v[178:179], s[48:49], v[34:35], v[162:163]
	v_cvt_pk_bf16_f32 v161, v174, v175
	v_cvt_pk_bf16_f32 v162, v168, v169
	v_fmac_f32_e32 v172, v174, v174
	v_mul_f32_e32 v169, v169, v169
	v_pk_fma_f32 v[170:171], s[48:49], v[42:43], v[170:171]
	v_add_f32_e32 v172, v173, v172
	v_fmac_f32_e32 v169, v168, v168
	v_add_f32_e32 v168, v169, v172
	v_mul_f32_e32 v169, v171, v171
	s_waitcnt vmcnt(10)
	v_pk_fma_f32 v[166:167], s[48:49], v[38:39], v[166:167]
	v_pk_fma_f32 v[164:165], s[42:43], v[36:37], v[164:165]
	v_fmac_f32_e32 v169, v170, v170
	v_cvt_pk_bf16_f32 v163, v170, v171
	v_add_f32_e32 v168, v169, v168
	v_mul_f32_e32 v169, v165, v165
	v_mul_f32_e32 v170, v167, v167
	v_fmac_f32_e32 v169, v164, v164
	v_fmac_f32_e32 v170, v166, v166
	v_add_f32_e32 v169, v169, v170
	v_mul_f32_e32 v170, v187, v187
	v_fmac_f32_e32 v170, v186, v186
	v_add_f32_e32 v169, v170, v169
	v_mul_f32_e32 v170, v179, v179
	v_fmac_f32_e32 v170, v178, v178
	v_add_f32_e32 v169, v170, v169
	v_add_f32_e32 v170, v168, v169
	v_mov_b32_e32 v171, v170
	s_nop 1
	v_permlane16_swap_b32_e32 v170, v171
	v_lshlrev_b64 v[182:183], 11, v[182:183]
	v_lshl_add_u64 v[168:169], s[64:65], 0, v[182:183]
	v_lshl_add_u64 v[168:169], v[200:201], 1, v[168:169]
	global_store_dwordx4 v[168:169], v[160:163], off
	s_waitcnt lgkmcnt(0)
	s_nop 0
	v_add_f32_e32 v160, v170, v171
	v_mov_b32_e32 v161, v160
	s_nop 1
	v_permlane32_swap_b32_e32 v160, v161
	v_cvt_pk_bf16_f32 v162, v164, v165
	v_cvt_pk_bf16_f32 v163, v166, v167
	v_cvt_pk_bf16_f32 v164, v186, v187
	v_cvt_pk_bf16_f32 v165, v178, v179
	global_store_dwordx4 v[168:169], v[162:165], off offset:256
	s_and_saveexec_b64 s[14:15], s[8:9]
	s_cbranch_execz .LBB0_378
	s_waitcnt lgkmcnt(0)
	v_add_f32_e32 v160, v160, v161
	v_fma_f32 v160, v160, s18, 0.5
	v_cvt_u32_f32_e32 v162, v160
	v_lshl_add_u64 v[160:161], v[202:203], 2, s[36:37]
	global_atomic_add v[160:161], v162, off offset:576
.LBB0_378:
	s_or_b64 exec, exec, s[14:15]
	s_waitcnt vmcnt(10)
	v_pk_fma_f32 v[156:157], s[42:43], v[28:29], v[156:157]
	v_pk_fma_f32 v[158:159], s[48:49], v[30:31], v[158:159]
	s_waitcnt vmcnt(9)
	v_pk_fma_f32 v[162:163], s[42:43], v[16:17], v[144:145]
	v_cvt_pk_bf16_f32 v144, v156, v157
	v_mul_f32_e32 v157, v157, v157
	v_pk_fma_f32 v[152:153], s[42:43], v[24:25], v[152:153]
	v_fmac_f32_e32 v157, v156, v156
	v_mul_f32_e32 v156, v159, v159
	s_waitcnt lgkmcnt(0)
	v_pk_fma_f32 v[160:161], s[48:49], v[18:19], v[146:147]
	v_cvt_pk_bf16_f32 v145, v158, v159
	v_cvt_pk_bf16_f32 v146, v152, v153
	v_fmac_f32_e32 v156, v158, v158
	v_mul_f32_e32 v153, v153, v153
	v_pk_fma_f32 v[154:155], s[48:49], v[26:27], v[154:155]
	v_add_f32_e32 v156, v157, v156
	v_fmac_f32_e32 v153, v152, v152
	v_add_f32_e32 v152, v153, v156
	v_mul_f32_e32 v153, v155, v155
	s_waitcnt vmcnt(8)
	v_pk_fma_f32 v[150:151], s[48:49], v[22:23], v[150:151]
	v_pk_fma_f32 v[148:149], s[42:43], v[20:21], v[148:149]
	v_fmac_f32_e32 v153, v154, v154
	v_cvt_pk_bf16_f32 v147, v154, v155
	v_add_f32_e32 v152, v153, v152
	v_mul_f32_e32 v153, v149, v149
	v_mul_f32_e32 v154, v151, v151
	v_fmac_f32_e32 v153, v148, v148
	v_fmac_f32_e32 v154, v150, v150
	v_add_f32_e32 v153, v153, v154
	v_mul_f32_e32 v154, v163, v163
	v_fmac_f32_e32 v154, v162, v162
	v_add_f32_e32 v153, v154, v153
	v_mul_f32_e32 v154, v161, v161
	v_fmac_f32_e32 v154, v160, v160
	v_add_f32_e32 v153, v154, v153
	v_add_f32_e32 v154, v152, v153
	v_mov_b32_e32 v155, v154
	s_nop 1
	v_permlane16_swap_b32_e32 v154, v155
	v_lshlrev_b64 v[164:165], 11, v[180:181]
	v_lshl_add_u64 v[152:153], s[64:65], 0, v[164:165]
	v_lshl_add_u64 v[152:153], v[200:201], 1, v[152:153]
	global_store_dwordx4 v[152:153], v[144:147], off
	s_waitcnt lgkmcnt(0)
	s_nop 0
	v_add_f32_e32 v144, v154, v155
	v_mov_b32_e32 v145, v144
	s_nop 1
	v_permlane32_swap_b32_e32 v144, v145
	v_cvt_pk_bf16_f32 v146, v148, v149
	v_cvt_pk_bf16_f32 v147, v150, v151
	v_cvt_pk_bf16_f32 v148, v162, v163
	v_cvt_pk_bf16_f32 v149, v160, v161
	global_store_dwordx4 v[152:153], v[146:149], off offset:256
	s_and_saveexec_b64 s[14:15], s[8:9]
	s_cbranch_execz .LBB0_380
	s_waitcnt lgkmcnt(0)
	v_add_f32_e32 v144, v144, v145
	v_fma_f32 v144, v144, s18, 0.5
	v_cvt_u32_f32_e32 v146, v144
	v_lshl_add_u64 v[144:145], v[202:203], 2, s[36:37]
	global_atomic_add v[144:145], v146, off offset:640
.LBB0_380:
	s_or_b64 exec, exec, s[14:15]
	s_waitcnt vmcnt(6) lgkmcnt(0)
	v_pk_fma_f32 v[144:145], s[42:43], v[4:5], v[132:133]
	v_lshlrev_b64 v[132:133], 11, v[204:205]
	v_lshl_add_u64 v[132:133], s[64:65], 0, v[132:133]
	v_pk_fma_f32 v[142:143], s[48:49], v[14:15], v[142:143]
	v_pk_fma_f32 v[140:141], s[42:43], v[12:13], v[140:141]
	v_pk_fma_f32 v[136:137], s[42:43], v[8:9], v[136:137]
	v_pk_fma_f32 v[146:147], s[48:49], v[2:3], v[130:131]
	v_pk_fma_f32 v[148:149], s[42:43], v[0:1], v[128:129]
	v_cvt_pk_bf16_f32 v128, v140, v141
	v_cvt_pk_bf16_f32 v129, v142, v143
	v_cvt_pk_bf16_f32 v130, v136, v137
	v_lshl_add_u64 v[150:151], v[200:201], 1, v[132:133]
	v_pk_fma_f32 v[138:139], s[48:49], v[10:11], v[138:139]
	v_pk_fma_f32 v[134:135], s[48:49], v[6:7], v[134:135]
	v_cvt_pk_bf16_f32 v131, v138, v139
	global_store_dwordx4 v[150:151], v[128:131], off
	s_mov_b64 s[14:15], s[8:9]
	s_nop 0
	v_cvt_pk_bf16_f32 v130, v144, v145
	v_mov_b32_e32 v129, v144
	v_mov_b32_e32 v144, v141
	v_mov_b32_e32 v128, v140
	v_pk_mul_f32 v[140:141], v[144:145], v[144:145]
	v_cvt_pk_bf16_f32 v131, v134, v135
	v_cvt_pk_bf16_f32 v132, v148, v149
	v_cvt_pk_bf16_f32 v133, v146, v147
	global_store_dwordx4 v[150:151], v[130:133], off offset:256
	v_pk_fma_f32 v[128:129], v[128:129], v[128:129], v[140:141]
	v_mov_b32_e32 v141, v134
	v_mov_b32_e32 v134, v143
	v_mov_b32_e32 v140, v142
	v_pk_mul_f32 v[134:135], v[134:135], v[134:135]
	s_nop 0
	v_pk_fma_f32 v[134:135], v[140:141], v[140:141], v[134:135]
	s_nop 0
	v_pk_add_f32 v[128:129], v[128:129], v[134:135]
	v_mov_b32_e32 v135, v148
	v_mov_b32_e32 v148, v137
	v_mov_b32_e32 v134, v136
	v_pk_mul_f32 v[136:137], v[148:149], v[148:149]
	s_nop 0
	v_pk_fma_f32 v[134:135], v[134:135], v[134:135], v[136:137]
	s_nop 0
	v_pk_add_f32 v[128:129], v[134:135], v[128:129]
	v_mov_b32_e32 v135, v146
	v_mov_b32_e32 v146, v139
	v_mov_b32_e32 v134, v138
	v_pk_mul_f32 v[136:137], v[146:147], v[146:147]
	s_nop 0
	v_pk_fma_f32 v[134:135], v[134:135], v[134:135], v[136:137]
	s_nop 0
	v_pk_add_f32 v[128:129], v[134:135], v[128:129]
	s_nop 0
	v_add_f32_e32 v128, v128, v129
	v_mov_b32_e32 v129, v128
	s_nop 1
	v_permlane16_swap_b32_e32 v128, v129
	s_waitcnt lgkmcnt(0)
	v_add_f32_e32 v128, v128, v129
	ds_bpermute_b32 v129, v215, v128

.LBB0_383:
	s_mov_b64 s[14:15], 0
	s_cbranch_execz .LBB0_381
	v_lshlrev_b64 v[186:187], 1, v[200:201]
	s_waitcnt lgkmcnt(0)
	v_lshl_add_u64 v[128:129], s[64:65], 0, v[186:187]
	v_lshl_add_u64 v[130:131], v[128:129], 0, v[208:209]
	global_load_dwordx4 v[226:229], v[130:131], off
	global_load_dwordx4 v[230:233], v[130:131], off offset:256
	v_ashrrev_i32_e32 v177, 31, v176
	v_lshlrev_b64 v[220:221], 11, v[176:177]
	v_ashrrev_i32_e32 v213, 31, v212
	v_lshl_add_u64 v[130:131], v[128:129], 0, v[220:221]
	v_lshlrev_b64 v[218:219], 11, v[212:213]
	v_ashrrev_i32_e32 v211, 31, v210
	global_load_dwordx4 v[180:183], v[130:131], off
	global_load_dwordx4 v[176:179], v[130:131], off offset:256
	v_lshl_add_u64 v[130:131], v[128:129], 0, v[218:219]
	v_lshlrev_b64 v[216:217], 11, v[210:211]
	global_load_dwordx4 v[172:175], v[130:131], off
	global_load_dwordx4 v[168:171], v[130:131], off offset:256
	v_lshl_add_u64 v[130:131], v[128:129], 0, v[216:217]
	v_lshl_add_u64 v[214:215], v[208:209], 0, s[92:93]
	s_mov_b64 s[14:15], 0x48000
	v_add_u32_e32 v204, 0xb0, v202
	global_load_dwordx4 v[164:167], v[130:131], off
	global_load_dwordx4 v[160:163], v[130:131], off offset:256
	v_lshl_add_u64 v[130:131], v[128:129], 0, v[214:215]
	v_lshl_add_u64 v[212:213], v[208:209], 0, s[14:15]
	s_mov_b64 s[14:15], 0x50000
	v_ashrrev_i32_e32 v205, 31, v204
	global_load_dwordx4 v[156:159], v[130:131], off
	global_load_dwordx4 v[152:155], v[130:131], off offset:256
	v_lshl_add_u64 v[130:131], v[128:129], 0, v[212:213]
	v_lshl_add_u64 v[210:211], v[208:209], 0, s[14:15]
	v_lshlrev_b64 v[208:209], 11, v[204:205]
	global_load_dwordx4 v[148:151], v[130:131], off
	global_load_dwordx4 v[144:147], v[130:131], off offset:256
	v_lshl_add_u64 v[130:131], v[128:129], 0, v[210:211]
	v_lshl_add_u64 v[128:129], v[128:129], 0, v[208:209]
	global_load_dwordx4 v[140:143], v[130:131], off
	global_load_dwordx4 v[136:139], v[130:131], off offset:256
	global_load_dwordx4 v[132:135], v[128:129], off
	s_nop 0
	global_load_dwordx4 v[128:131], v[128:129], off offset:256
	v_lshl_add_u64 v[186:187], v[206:207], 0, v[186:187]
	s_waitcnt vmcnt(0)
	v_lshlrev_b32_e32 v188, 16, v226
	v_and_b32_e32 v189, 0xffff0000, v226
	v_lshlrev_b32_e32 v226, 16, v227
	v_and_b32_e32 v227, 0xffff0000, v227
	v_lshlrev_b32_e32 v234, 16, v228
	v_and_b32_e32 v235, 0xffff0000, v228
	v_lshlrev_b32_e32 v228, 16, v229
	v_and_b32_e32 v229, 0xffff0000, v229
	v_pk_fma_f32 v[126:127], s[48:49], v[126:127], v[226:227]
	v_pk_fma_f32 v[122:123], s[48:49], v[122:123], v[228:229]
	v_lshlrev_b32_e32 v226, 16, v231
	v_and_b32_e32 v227, 0xffff0000, v231
	v_lshlrev_b32_e32 v228, 16, v232
	v_and_b32_e32 v229, 0xffff0000, v232
	v_pk_fma_f32 v[124:125], s[42:43], v[124:125], v[188:189]
	v_lshlrev_b32_e32 v188, 16, v230
	v_and_b32_e32 v189, 0xffff0000, v230
	v_lshlrev_b32_e32 v230, 16, v233
	v_and_b32_e32 v231, 0xffff0000, v233
	v_pk_fma_f32 v[118:119], s[48:49], v[118:119], v[226:227]
	v_pk_fma_f32 v[226:227], s[42:43], v[112:113], v[228:229]
	v_cvt_pk_bf16_f32 v112, v124, v125
	v_cvt_pk_bf16_f32 v113, v126, v127
	v_pk_fma_f32 v[120:121], s[42:43], v[120:121], v[234:235]
	v_pk_fma_f32 v[116:117], s[42:43], v[116:117], v[188:189]
	v_pk_fma_f32 v[188:189], s[48:49], v[114:115], v[230:231]
	v_cvt_pk_bf16_f32 v114, v120, v121
	v_cvt_pk_bf16_f32 v115, v122, v123
	global_store_dwordx4 v[186:187], v[112:115], off
	s_nop 1
	v_mul_f32_e32 v112, v125, v125
	v_mul_f32_e32 v113, v127, v127
	v_fmac_f32_e32 v112, v124, v124
	v_fmac_f32_e32 v113, v126, v126
	v_add_f32_e32 v112, v112, v113
	v_mul_f32_e32 v113, v121, v121
	v_fmac_f32_e32 v113, v120, v120
	v_add_f32_e32 v112, v113, v112
	v_mul_f32_e32 v113, v123, v123
	v_fmac_f32_e32 v113, v122, v122
	v_add_f32_e32 v120, v113, v112
	v_cvt_pk_bf16_f32 v112, v116, v117
	v_cvt_pk_bf16_f32 v113, v118, v119
	v_cvt_pk_bf16_f32 v114, v226, v227
	v_cvt_pk_bf16_f32 v115, v188, v189
	global_store_dwordx4 v[186:187], v[112:115], off offset:256
	s_nop 1
	v_mul_f32_e32 v112, v117, v117
	v_mul_f32_e32 v113, v119, v119
	v_fmac_f32_e32 v112, v116, v116
	v_fmac_f32_e32 v113, v118, v118
	v_add_f32_e32 v112, v112, v113
	v_mul_f32_e32 v113, v227, v227
	v_fmac_f32_e32 v113, v226, v226
	v_add_f32_e32 v112, v113, v112
	v_mul_f32_e32 v113, v189, v189
	v_fmac_f32_e32 v113, v188, v188
	v_and_b32_e32 v114, 64, v243
	v_add_f32_e32 v112, v113, v112
	v_xor_b32_e32 v113, 16, v243
	v_add_u32_e32 v115, 64, v114
	v_cmp_lt_i32_e32 vcc, v113, v115
	v_add_f32_e32 v112, v120, v112
	s_nop 0
	v_cndmask_b32_e32 v113, v243, v113, vcc
	v_lshlrev_b32_e32 v114, 2, v113
	v_mov_b32_e32 v113, v112
	s_nop 1
	v_permlane16_swap_b32_e32 v112, v113
	s_waitcnt lgkmcnt(0)
	v_add_f32_e32 v116, v112, v113
	v_xor_b32_e32 v112, 32, v243
	v_cmp_lt_i32_e32 vcc, v112, v115
	s_nop 1
	v_cndmask_b32_e32 v112, v243, v112, vcc
	v_lshlrev_b32_e32 v115, 2, v112
	v_mov_b32_e32 v117, v116
	s_nop 1
	v_permlane32_swap_b32_e32 v116, v117
	v_lshl_add_u64 v[112:113], v[202:203], 2, s[36:37]
	s_and_saveexec_b64 s[14:15], s[8:9]
	s_cbranch_execz .LBB0_386
	s_waitcnt lgkmcnt(0)
	v_add_f32_e32 v116, v116, v117
	v_fma_f32 v116, v116, s18, 0.5
	v_cvt_u32_f32_e32 v116, v116
	global_atomic_add v[112:113], v116, off
.LBB0_386:
	s_or_b64 exec, exec, s[14:15]
	v_lshlrev_b32_e32 v116, 16, v180
	s_waitcnt lgkmcnt(0)
	v_and_b32_e32 v117, 0xffff0000, v180
	v_lshlrev_b32_e32 v118, 16, v181
	v_and_b32_e32 v119, 0xffff0000, v181
	v_lshlrev_b32_e32 v120, 16, v182
	v_and_b32_e32 v121, 0xffff0000, v182
	v_pk_fma_f32 v[110:111], s[48:49], v[110:111], v[118:119]
	v_pk_fma_f32 v[108:109], s[42:43], v[108:109], v[116:117]
	v_pk_fma_f32 v[104:105], s[42:43], v[104:105], v[120:121]
	v_lshlrev_b32_e32 v118, 16, v177
	v_and_b32_e32 v119, 0xffff0000, v177
	v_lshlrev_b32_e32 v120, 16, v178
	v_and_b32_e32 v121, 0xffff0000, v178
	v_lshlrev_b32_e32 v122, 16, v183
	v_and_b32_e32 v123, 0xffff0000, v183
	v_pk_fma_f32 v[102:103], s[48:49], v[102:103], v[118:119]
	v_pk_fma_f32 v[118:119], s[42:43], v[96:97], v[120:121]
	v_cvt_pk_bf16_f32 v96, v108, v109
	v_mul_f32_e32 v109, v109, v109
	v_pk_fma_f32 v[106:107], s[48:49], v[106:107], v[122:123]
	v_lshlrev_b32_e32 v116, 16, v176
	v_and_b32_e32 v117, 0xffff0000, v176
	v_lshlrev_b32_e32 v122, 16, v179
	v_and_b32_e32 v123, 0xffff0000, v179
	v_fmac_f32_e32 v109, v108, v108
	v_mul_f32_e32 v108, v111, v111
	v_pk_fma_f32 v[100:101], s[42:43], v[100:101], v[116:117]
	v_pk_fma_f32 v[116:117], s[48:49], v[98:99], v[122:123]
	v_cvt_pk_bf16_f32 v97, v110, v111
	v_cvt_pk_bf16_f32 v98, v104, v105
	v_fmac_f32_e32 v108, v110, v110
	v_mul_f32_e32 v105, v105, v105
	v_add_f32_e32 v108, v109, v108
	v_fmac_f32_e32 v105, v104, v104
	v_add_f32_e32 v104, v105, v108
	v_mul_f32_e32 v105, v107, v107
	v_fmac_f32_e32 v105, v106, v106
	v_cvt_pk_bf16_f32 v99, v106, v107
	v_add_f32_e32 v104, v105, v104
	v_mul_f32_e32 v105, v101, v101
	v_mul_f32_e32 v106, v103, v103
	v_fmac_f32_e32 v105, v100, v100
	v_fmac_f32_e32 v106, v102, v102
	v_add_f32_e32 v105, v105, v106
	v_mul_f32_e32 v106, v119, v119
	v_fmac_f32_e32 v106, v118, v118
	v_add_f32_e32 v105, v106, v105
	v_mul_f32_e32 v106, v117, v117
	v_fmac_f32_e32 v106, v116, v116
	v_add_f32_e32 v105, v106, v105
	v_add_f32_e32 v106, v104, v105
	v_mov_b32_e32 v107, v106
	s_nop 1
	v_permlane16_swap_b32_e32 v106, v107
	v_lshl_add_u64 v[104:105], s[64:65], 0, v[220:221]
	v_lshl_add_u64 v[104:105], v[200:201], 1, v[104:105]
	global_store_dwordx4 v[104:105], v[96:99], off
	s_waitcnt lgkmcnt(0)
	s_nop 0
	v_add_f32_e32 v96, v106, v107
	v_mov_b32_e32 v97, v96
	s_nop 1
	v_permlane32_swap_b32_e32 v96, v97
	v_cvt_pk_bf16_f32 v98, v100, v101
	v_cvt_pk_bf16_f32 v99, v102, v103
	v_cvt_pk_bf16_f32 v100, v118, v119
	v_cvt_pk_bf16_f32 v101, v116, v117
	global_store_dwordx4 v[104:105], v[98:101], off offset:256
	s_and_saveexec_b64 s[14:15], s[8:9]
	s_cbranch_execz .LBB0_388
	s_waitcnt lgkmcnt(0)
	v_add_f32_e32 v96, v96, v97
	v_fma_f32 v96, v96, s18, 0.5
	v_cvt_u32_f32_e32 v96, v96
	global_atomic_add v[112:113], v96, off offset:64
.LBB0_388:
	s_or_b64 exec, exec, s[14:15]
	v_lshlrev_b32_e32 v96, 16, v172
	s_waitcnt lgkmcnt(0)
	v_and_b32_e32 v97, 0xffff0000, v172
	v_lshlrev_b32_e32 v98, 16, v173
	v_and_b32_e32 v99, 0xffff0000, v173
	v_lshlrev_b32_e32 v100, 16, v174
	v_and_b32_e32 v101, 0xffff0000, v174
	v_pk_fma_f32 v[94:95], s[48:49], v[94:95], v[98:99]
	v_pk_fma_f32 v[92:93], s[42:43], v[92:93], v[96:97]
	v_pk_fma_f32 v[88:89], s[42:43], v[88:89], v[100:101]
	v_lshlrev_b32_e32 v98, 16, v169
	v_and_b32_e32 v99, 0xffff0000, v169
	v_lshlrev_b32_e32 v100, 16, v170
	v_and_b32_e32 v101, 0xffff0000, v170
	v_lshlrev_b32_e32 v102, 16, v175
	v_and_b32_e32 v103, 0xffff0000, v175
	v_pk_fma_f32 v[86:87], s[48:49], v[86:87], v[98:99]
	v_pk_fma_f32 v[98:99], s[42:43], v[80:81], v[100:101]
	v_cvt_pk_bf16_f32 v80, v92, v93
	v_mul_f32_e32 v93, v93, v93
	v_pk_fma_f32 v[90:91], s[48:49], v[90:91], v[102:103]
	v_lshlrev_b32_e32 v96, 16, v168
	v_and_b32_e32 v97, 0xffff0000, v168
	v_lshlrev_b32_e32 v102, 16, v171
	v_and_b32_e32 v103, 0xffff0000, v171
	v_fmac_f32_e32 v93, v92, v92
	v_mul_f32_e32 v92, v95, v95
	v_pk_fma_f32 v[84:85], s[42:43], v[84:85], v[96:97]
	v_pk_fma_f32 v[96:97], s[48:49], v[82:83], v[102:103]
	v_cvt_pk_bf16_f32 v81, v94, v95
	v_cvt_pk_bf16_f32 v82, v88, v89
	v_fmac_f32_e32 v92, v94, v94
	v_mul_f32_e32 v89, v89, v89
	v_add_f32_e32 v92, v93, v92
	v_fmac_f32_e32 v89, v88, v88
	v_add_f32_e32 v88, v89, v92
	v_mul_f32_e32 v89, v91, v91
	v_fmac_f32_e32 v89, v90, v90
	v_cvt_pk_bf16_f32 v83, v90, v91
	v_add_f32_e32 v88, v89, v88
	v_mul_f32_e32 v89, v85, v85
	v_mul_f32_e32 v90, v87, v87
	v_fmac_f32_e32 v89, v84, v84
	v_fmac_f32_e32 v90, v86, v86
	v_add_f32_e32 v89, v89, v90
	v_mul_f32_e32 v90, v99, v99
	v_fmac_f32_e32 v90, v98, v98
	v_add_f32_e32 v89, v90, v89
	v_mul_f32_e32 v90, v97, v97
	v_fmac_f32_e32 v90, v96, v96
	v_add_f32_e32 v89, v90, v89
	v_add_f32_e32 v90, v88, v89
	v_mov_b32_e32 v91, v90
	s_nop 1
	v_permlane16_swap_b32_e32 v90, v91
	v_lshl_add_u64 v[88:89], s[64:65], 0, v[218:219]
	v_lshl_add_u64 v[88:89], v[200:201], 1, v[88:89]
	global_store_dwordx4 v[88:89], v[80:83], off
	s_waitcnt lgkmcnt(0)
	s_nop 0
	v_add_f32_e32 v80, v90, v91
	v_mov_b32_e32 v81, v80
	s_nop 1
	v_permlane32_swap_b32_e32 v80, v81
	v_cvt_pk_bf16_f32 v82, v84, v85
	v_cvt_pk_bf16_f32 v83, v86, v87
	v_cvt_pk_bf16_f32 v84, v98, v99
	v_cvt_pk_bf16_f32 v85, v96, v97
	global_store_dwordx4 v[88:89], v[82:85], off offset:256
	s_and_saveexec_b64 s[14:15], s[8:9]
	s_cbranch_execz .LBB0_390
	s_waitcnt lgkmcnt(0)
	v_add_f32_e32 v80, v80, v81
	v_fma_f32 v80, v80, s18, 0.5
	v_cvt_u32_f32_e32 v80, v80
	global_atomic_add v[112:113], v80, off offset:128
.LBB0_390:
	s_or_b64 exec, exec, s[14:15]
	v_lshlrev_b32_e32 v80, 16, v164
	s_waitcnt lgkmcnt(0)
	v_and_b32_e32 v81, 0xffff0000, v164
	v_lshlrev_b32_e32 v82, 16, v165
	v_and_b32_e32 v83, 0xffff0000, v165
	v_lshlrev_b32_e32 v84, 16, v166
	v_and_b32_e32 v85, 0xffff0000, v166
	v_pk_fma_f32 v[78:79], s[48:49], v[78:79], v[82:83]
	v_pk_fma_f32 v[76:77], s[42:43], v[76:77], v[80:81]
	v_pk_fma_f32 v[72:73], s[42:43], v[72:73], v[84:85]
	v_lshlrev_b32_e32 v82, 16, v161
	v_and_b32_e32 v83, 0xffff0000, v161
	v_lshlrev_b32_e32 v84, 16, v162
	v_and_b32_e32 v85, 0xffff0000, v162
	v_lshlrev_b32_e32 v86, 16, v167
	v_and_b32_e32 v87, 0xffff0000, v167
	v_pk_fma_f32 v[70:71], s[48:49], v[70:71], v[82:83]
	v_pk_fma_f32 v[82:83], s[42:43], v[64:65], v[84:85]
	v_cvt_pk_bf16_f32 v64, v76, v77
	v_mul_f32_e32 v77, v77, v77
	v_pk_fma_f32 v[74:75], s[48:49], v[74:75], v[86:87]
	v_lshlrev_b32_e32 v80, 16, v160
	v_and_b32_e32 v81, 0xffff0000, v160
	v_lshlrev_b32_e32 v86, 16, v163
	v_and_b32_e32 v87, 0xffff0000, v163
	v_fmac_f32_e32 v77, v76, v76
	v_mul_f32_e32 v76, v79, v79
	v_pk_fma_f32 v[68:69], s[42:43], v[68:69], v[80:81]
	v_pk_fma_f32 v[80:81], s[48:49], v[66:67], v[86:87]
	v_cvt_pk_bf16_f32 v65, v78, v79
	v_cvt_pk_bf16_f32 v66, v72, v73
	v_fmac_f32_e32 v76, v78, v78
	v_mul_f32_e32 v73, v73, v73
	v_add_f32_e32 v76, v77, v76
	v_fmac_f32_e32 v73, v72, v72
	v_add_f32_e32 v72, v73, v76
	v_mul_f32_e32 v73, v75, v75
	v_fmac_f32_e32 v73, v74, v74
	v_cvt_pk_bf16_f32 v67, v74, v75
	v_add_f32_e32 v72, v73, v72
	v_mul_f32_e32 v73, v69, v69
	v_mul_f32_e32 v74, v71, v71
	v_fmac_f32_e32 v73, v68, v68
	v_fmac_f32_e32 v74, v70, v70
	v_add_f32_e32 v73, v73, v74
	v_mul_f32_e32 v74, v83, v83
	v_fmac_f32_e32 v74, v82, v82
	v_add_f32_e32 v73, v74, v73
	v_mul_f32_e32 v74, v81, v81
	v_fmac_f32_e32 v74, v80, v80
	v_add_f32_e32 v73, v74, v73
	v_add_f32_e32 v74, v72, v73
	v_mov_b32_e32 v75, v74
	s_nop 1
	v_permlane16_swap_b32_e32 v74, v75
	v_lshl_add_u64 v[72:73], s[64:65], 0, v[216:217]
	v_lshl_add_u64 v[72:73], v[200:201], 1, v[72:73]
	global_store_dwordx4 v[72:73], v[64:67], off
	s_waitcnt lgkmcnt(0)
	s_nop 0
	v_add_f32_e32 v64, v74, v75
	v_mov_b32_e32 v65, v64
	s_nop 1
	v_permlane32_swap_b32_e32 v64, v65
	v_cvt_pk_bf16_f32 v66, v68, v69
	v_cvt_pk_bf16_f32 v67, v70, v71
	v_cvt_pk_bf16_f32 v68, v82, v83
	v_cvt_pk_bf16_f32 v69, v80, v81
	global_store_dwordx4 v[72:73], v[66:69], off offset:256
	s_and_saveexec_b64 s[14:15], s[8:9]
	s_cbranch_execz .LBB0_392
	s_waitcnt lgkmcnt(0)
	v_add_f32_e32 v64, v64, v65
	v_fma_f32 v64, v64, s18, 0.5
	v_cvt_u32_f32_e32 v64, v64
	global_atomic_add v[112:113], v64, off offset:192
.LBB0_392:
	s_or_b64 exec, exec, s[14:15]
	v_lshlrev_b32_e32 v64, 16, v156
	s_waitcnt lgkmcnt(0)
	v_and_b32_e32 v65, 0xffff0000, v156
	v_lshlrev_b32_e32 v66, 16, v157
	v_and_b32_e32 v67, 0xffff0000, v157
	v_lshlrev_b32_e32 v68, 16, v158
	v_and_b32_e32 v69, 0xffff0000, v158
	v_pk_fma_f32 v[62:63], s[48:49], v[62:63], v[66:67]
	v_pk_fma_f32 v[60:61], s[42:43], v[60:61], v[64:65]
	v_pk_fma_f32 v[56:57], s[42:43], v[56:57], v[68:69]
	v_lshlrev_b32_e32 v66, 16, v153
	v_and_b32_e32 v67, 0xffff0000, v153
	v_lshlrev_b32_e32 v68, 16, v154
	v_and_b32_e32 v69, 0xffff0000, v154
	v_lshlrev_b32_e32 v70, 16, v159
	v_and_b32_e32 v71, 0xffff0000, v159
	v_pk_fma_f32 v[54:55], s[48:49], v[54:55], v[66:67]
	v_pk_fma_f32 v[66:67], s[42:43], v[48:49], v[68:69]
	v_cvt_pk_bf16_f32 v48, v60, v61
	v_mul_f32_e32 v61, v61, v61
	v_pk_fma_f32 v[58:59], s[48:49], v[58:59], v[70:71]
	v_lshlrev_b32_e32 v64, 16, v152
	v_and_b32_e32 v65, 0xffff0000, v152
	v_lshlrev_b32_e32 v70, 16, v155
	v_and_b32_e32 v71, 0xffff0000, v155
	v_fmac_f32_e32 v61, v60, v60
	v_mul_f32_e32 v60, v63, v63
	v_pk_fma_f32 v[52:53], s[42:43], v[52:53], v[64:65]
	v_pk_fma_f32 v[64:65], s[48:49], v[50:51], v[70:71]
	v_cvt_pk_bf16_f32 v49, v62, v63
	v_cvt_pk_bf16_f32 v50, v56, v57
	v_fmac_f32_e32 v60, v62, v62
	v_mul_f32_e32 v57, v57, v57
	v_add_f32_e32 v60, v61, v60
	v_fmac_f32_e32 v57, v56, v56
	v_add_f32_e32 v56, v57, v60
	v_mul_f32_e32 v57, v59, v59
	v_fmac_f32_e32 v57, v58, v58
	v_cvt_pk_bf16_f32 v51, v58, v59
	v_add_f32_e32 v56, v57, v56
	v_mul_f32_e32 v57, v53, v53
	v_mul_f32_e32 v58, v55, v55
	v_fmac_f32_e32 v57, v52, v52
	v_fmac_f32_e32 v58, v54, v54
	v_add_f32_e32 v57, v57, v58
	v_mul_f32_e32 v58, v67, v67
	v_fmac_f32_e32 v58, v66, v66
	v_add_f32_e32 v57, v58, v57
	v_mul_f32_e32 v58, v65, v65
	v_fmac_f32_e32 v58, v64, v64
	v_add_f32_e32 v57, v58, v57
	v_add_f32_e32 v58, v56, v57
	v_mov_b32_e32 v59, v58
	s_nop 1
	v_permlane16_swap_b32_e32 v58, v59
	v_lshl_add_u64 v[56:57], s[64:65], 0, v[214:215]
	v_lshl_add_u64 v[56:57], v[200:201], 1, v[56:57]
	global_store_dwordx4 v[56:57], v[48:51], off
	s_waitcnt lgkmcnt(0)
	s_nop 0
	v_add_f32_e32 v48, v58, v59
	v_mov_b32_e32 v49, v48
	s_nop 1
	v_permlane32_swap_b32_e32 v48, v49
	v_cvt_pk_bf16_f32 v50, v52, v53
	v_cvt_pk_bf16_f32 v51, v54, v55
	v_cvt_pk_bf16_f32 v52, v66, v67
	v_cvt_pk_bf16_f32 v53, v64, v65
	global_store_dwordx4 v[56:57], v[50:53], off offset:256
	s_and_saveexec_b64 s[14:15], s[8:9]
	s_cbranch_execz .LBB0_394
	s_waitcnt lgkmcnt(0)
	v_add_f32_e32 v48, v48, v49
	v_fma_f32 v48, v48, s18, 0.5
	v_cvt_u32_f32_e32 v48, v48
	global_atomic_add v[112:113], v48, off offset:512
.LBB0_394:
	s_or_b64 exec, exec, s[14:15]
	v_lshlrev_b32_e32 v48, 16, v148
	s_waitcnt lgkmcnt(0)
	v_and_b32_e32 v49, 0xffff0000, v148
	v_lshlrev_b32_e32 v50, 16, v149
	v_and_b32_e32 v51, 0xffff0000, v149
	v_lshlrev_b32_e32 v52, 16, v150
	v_and_b32_e32 v53, 0xffff0000, v150
	v_pk_fma_f32 v[46:47], s[48:49], v[46:47], v[50:51]
	v_pk_fma_f32 v[44:45], s[42:43], v[44:45], v[48:49]
	v_pk_fma_f32 v[40:41], s[42:43], v[40:41], v[52:53]
	v_lshlrev_b32_e32 v50, 16, v145
	v_and_b32_e32 v51, 0xffff0000, v145
	v_lshlrev_b32_e32 v52, 16, v146
	v_and_b32_e32 v53, 0xffff0000, v146
	v_lshlrev_b32_e32 v54, 16, v151
	v_and_b32_e32 v55, 0xffff0000, v151
	v_pk_fma_f32 v[38:39], s[48:49], v[38:39], v[50:51]
	v_pk_fma_f32 v[50:51], s[42:43], v[32:33], v[52:53]
	v_cvt_pk_bf16_f32 v32, v44, v45
	v_mul_f32_e32 v45, v45, v45
	v_pk_fma_f32 v[42:43], s[48:49], v[42:43], v[54:55]
	v_lshlrev_b32_e32 v48, 16, v144
	v_and_b32_e32 v49, 0xffff0000, v144
	v_lshlrev_b32_e32 v54, 16, v147
	v_and_b32_e32 v55, 0xffff0000, v147
	v_fmac_f32_e32 v45, v44, v44
	v_mul_f32_e32 v44, v47, v47
	v_pk_fma_f32 v[36:37], s[42:43], v[36:37], v[48:49]
	v_pk_fma_f32 v[48:49], s[48:49], v[34:35], v[54:55]
	v_cvt_pk_bf16_f32 v33, v46, v47
	v_cvt_pk_bf16_f32 v34, v40, v41
	v_fmac_f32_e32 v44, v46, v46
	v_mul_f32_e32 v41, v41, v41
	v_add_f32_e32 v44, v45, v44
	v_fmac_f32_e32 v41, v40, v40
	v_add_f32_e32 v40, v41, v44
	v_mul_f32_e32 v41, v43, v43
	v_fmac_f32_e32 v41, v42, v42
	v_cvt_pk_bf16_f32 v35, v42, v43
	v_add_f32_e32 v40, v41, v40
	v_mul_f32_e32 v41, v37, v37
	v_mul_f32_e32 v42, v39, v39
	v_fmac_f32_e32 v41, v36, v36
	v_fmac_f32_e32 v42, v38, v38
	v_add_f32_e32 v41, v41, v42
	v_mul_f32_e32 v42, v51, v51
	v_fmac_f32_e32 v42, v50, v50
	v_add_f32_e32 v41, v42, v41
	v_mul_f32_e32 v42, v49, v49
	v_fmac_f32_e32 v42, v48, v48
	v_add_f32_e32 v41, v42, v41
	v_add_f32_e32 v42, v40, v41
	v_mov_b32_e32 v43, v42
	s_nop 1
	v_permlane16_swap_b32_e32 v42, v43
	v_lshl_add_u64 v[40:41], s[64:65], 0, v[212:213]
	v_lshl_add_u64 v[40:41], v[200:201], 1, v[40:41]
	global_store_dwordx4 v[40:41], v[32:35], off
	s_waitcnt lgkmcnt(0)
	s_nop 0
	v_add_f32_e32 v32, v42, v43
	v_mov_b32_e32 v33, v32
	s_nop 1
	v_permlane32_swap_b32_e32 v32, v33
	v_cvt_pk_bf16_f32 v34, v36, v37
	v_cvt_pk_bf16_f32 v35, v38, v39
	v_cvt_pk_bf16_f32 v36, v50, v51
	v_cvt_pk_bf16_f32 v37, v48, v49
	global_store_dwordx4 v[40:41], v[34:37], off offset:256
	s_and_saveexec_b64 s[14:15], s[8:9]
	s_cbranch_execz .LBB0_396
	s_waitcnt lgkmcnt(0)
	v_add_f32_e32 v32, v32, v33
	v_fma_f32 v32, v32, s18, 0.5
	v_cvt_u32_f32_e32 v32, v32
	global_atomic_add v[112:113], v32, off offset:576
.LBB0_396:
	s_or_b64 exec, exec, s[14:15]
	v_lshlrev_b32_e32 v32, 16, v140
	s_waitcnt lgkmcnt(0)
	v_and_b32_e32 v33, 0xffff0000, v140
	v_lshlrev_b32_e32 v34, 16, v141
	v_and_b32_e32 v35, 0xffff0000, v141
	v_lshlrev_b32_e32 v36, 16, v142
	v_and_b32_e32 v37, 0xffff0000, v142
	v_pk_fma_f32 v[30:31], s[48:49], v[30:31], v[34:35]
	v_pk_fma_f32 v[28:29], s[42:43], v[28:29], v[32:33]
	v_pk_fma_f32 v[24:25], s[42:43], v[24:25], v[36:37]
	v_lshlrev_b32_e32 v34, 16, v137
	v_and_b32_e32 v35, 0xffff0000, v137
	v_lshlrev_b32_e32 v36, 16, v138
	v_and_b32_e32 v37, 0xffff0000, v138
	v_lshlrev_b32_e32 v38, 16, v143
	v_and_b32_e32 v39, 0xffff0000, v143
	v_pk_fma_f32 v[22:23], s[48:49], v[22:23], v[34:35]
	v_pk_fma_f32 v[34:35], s[42:43], v[16:17], v[36:37]
	v_cvt_pk_bf16_f32 v16, v28, v29
	v_mul_f32_e32 v29, v29, v29
	v_pk_fma_f32 v[26:27], s[48:49], v[26:27], v[38:39]
	v_lshlrev_b32_e32 v32, 16, v136
	v_and_b32_e32 v33, 0xffff0000, v136
	v_lshlrev_b32_e32 v38, 16, v139
	v_and_b32_e32 v39, 0xffff0000, v139
	v_fmac_f32_e32 v29, v28, v28
	v_mul_f32_e32 v28, v31, v31
	v_pk_fma_f32 v[20:21], s[42:43], v[20:21], v[32:33]
	v_pk_fma_f32 v[32:33], s[48:49], v[18:19], v[38:39]
	v_cvt_pk_bf16_f32 v17, v30, v31
	v_cvt_pk_bf16_f32 v18, v24, v25
	v_fmac_f32_e32 v28, v30, v30
	v_mul_f32_e32 v25, v25, v25
	v_add_f32_e32 v28, v29, v28
	v_fmac_f32_e32 v25, v24, v24
	v_add_f32_e32 v24, v25, v28
	v_mul_f32_e32 v25, v27, v27
	v_fmac_f32_e32 v25, v26, v26
	v_cvt_pk_bf16_f32 v19, v26, v27
	v_add_f32_e32 v24, v25, v24
	v_mul_f32_e32 v25, v21, v21
	v_mul_f32_e32 v26, v23, v23
	v_fmac_f32_e32 v25, v20, v20
	v_fmac_f32_e32 v26, v22, v22
	v_add_f32_e32 v25, v25, v26
	v_mul_f32_e32 v26, v35, v35
	v_fmac_f32_e32 v26, v34, v34
	v_add_f32_e32 v25, v26, v25
	v_mul_f32_e32 v26, v33, v33
	v_fmac_f32_e32 v26, v32, v32
	v_add_f32_e32 v25, v26, v25
	v_add_f32_e32 v26, v24, v25
	v_mov_b32_e32 v27, v26
	s_nop 1
	v_permlane16_swap_b32_e32 v26, v27
	v_lshl_add_u64 v[24:25], s[64:65], 0, v[210:211]
	v_lshl_add_u64 v[24:25], v[200:201], 1, v[24:25]
	global_store_dwordx4 v[24:25], v[16:19], off
	s_waitcnt lgkmcnt(0)
	s_nop 0
	v_add_f32_e32 v16, v26, v27
	v_mov_b32_e32 v17, v16
	s_nop 1
	v_permlane32_swap_b32_e32 v16, v17
	v_cvt_pk_bf16_f32 v18, v20, v21
	v_cvt_pk_bf16_f32 v19, v22, v23
	v_cvt_pk_bf16_f32 v20, v34, v35
	v_cvt_pk_bf16_f32 v21, v32, v33
	global_store_dwordx4 v[24:25], v[18:21], off offset:256
	s_and_saveexec_b64 s[14:15], s[8:9]
	s_cbranch_execz .LBB0_398
	s_waitcnt lgkmcnt(0)
	v_add_f32_e32 v16, v16, v17
	v_fma_f32 v16, v16, s18, 0.5
	v_cvt_u32_f32_e32 v16, v16
	global_atomic_add v[112:113], v16, off offset:640
.LBB0_398:
	s_or_b64 exec, exec, s[14:15]
	v_lshlrev_b32_e32 v18, 16, v133
	v_and_b32_e32 v19, 0xffff0000, v133
	v_lshlrev_b32_e32 v20, 16, v134
	v_and_b32_e32 v21, 0xffff0000, v134
	v_lshlrev_b32_e32 v16, 16, v132
	s_waitcnt lgkmcnt(0)
	v_and_b32_e32 v17, 0xffff0000, v132
	v_pk_fma_f32 v[14:15], s[48:49], v[14:15], v[18:19]
	v_pk_fma_f32 v[8:9], s[42:43], v[8:9], v[20:21]
	v_lshlrev_b32_e32 v18, 16, v129
	v_and_b32_e32 v19, 0xffff0000, v129
	v_lshlrev_b32_e32 v20, 16, v130
	v_and_b32_e32 v21, 0xffff0000, v130
	v_lshlrev_b32_e32 v22, 16, v135
	v_and_b32_e32 v23, 0xffff0000, v135
	v_pk_fma_f32 v[12:13], s[42:43], v[12:13], v[16:17]
	v_lshlrev_b32_e32 v16, 16, v128
	v_and_b32_e32 v17, 0xffff0000, v128
	v_pk_fma_f32 v[6:7], s[48:49], v[6:7], v[18:19]
	v_pk_fma_f32 v[18:19], s[42:43], v[0:1], v[20:21]
	v_lshl_add_u64 v[20:21], s[64:65], 0, v[208:209]
	v_pk_fma_f32 v[10:11], s[48:49], v[10:11], v[22:23]
	v_lshlrev_b32_e32 v22, 16, v131
	v_and_b32_e32 v23, 0xffff0000, v131
	v_pk_fma_f32 v[4:5], s[42:43], v[4:5], v[16:17]
	v_cvt_pk_bf16_f32 v0, v12, v13
	v_cvt_pk_bf16_f32 v1, v14, v15
	v_lshl_add_u64 v[20:21], v[200:201], 1, v[20:21]
	v_pk_fma_f32 v[16:17], s[48:49], v[2:3], v[22:23]
	v_cvt_pk_bf16_f32 v2, v8, v9
	v_cvt_pk_bf16_f32 v3, v10, v11
	global_store_dwordx4 v[20:21], v[0:3], off
	v_mov_b32_e32 v23, v4
	v_mov_b32_e32 v22, v12
	v_cvt_pk_bf16_f32 v0, v4, v5
	v_cvt_pk_bf16_f32 v1, v6, v7
	v_mov_b32_e32 v4, v13
	v_mov_b32_e32 v13, v6
	v_mov_b32_e32 v6, v15
	v_pk_mul_f32 v[4:5], v[4:5], v[4:5]
	v_mov_b32_e32 v12, v14
	v_pk_mul_f32 v[6:7], v[6:7], v[6:7]
	v_pk_fma_f32 v[4:5], v[22:23], v[22:23], v[4:5]
	v_pk_fma_f32 v[6:7], v[12:13], v[12:13], v[6:7]
	v_cvt_pk_bf16_f32 v2, v18, v19
	v_cvt_pk_bf16_f32 v3, v16, v17
	s_mov_b64 s[14:15], s[8:9]
	v_pk_add_f32 v[4:5], v[4:5], v[6:7]
	v_mov_b32_e32 v7, v18
	v_mov_b32_e32 v18, v9
	v_mov_b32_e32 v6, v8
	v_pk_mul_f32 v[8:9], v[18:19], v[18:19]
	global_store_dwordx4 v[20:21], v[0:3], off offset:256
	v_pk_fma_f32 v[6:7], v[6:7], v[6:7], v[8:9]
	s_nop 0
	v_pk_add_f32 v[4:5], v[6:7], v[4:5]
	v_mov_b32_e32 v7, v16
	v_mov_b32_e32 v16, v11
	v_mov_b32_e32 v6, v10
	v_pk_mul_f32 v[8:9], v[16:17], v[16:17]
	s_nop 0
	v_pk_fma_f32 v[6:7], v[6:7], v[6:7], v[8:9]
	s_nop 0
	v_pk_add_f32 v[4:5], v[6:7], v[4:5]
	s_nop 0
	v_add_f32_e32 v4, v4, v5
	v_mov_b32_e32 v5, v4
	s_nop 1
	v_permlane16_swap_b32_e32 v4, v5
	s_waitcnt lgkmcnt(0)
	v_add_f32_e32 v128, v4, v5
	v_mov_b32_e32 v129, v128
	s_nop 1
	v_permlane32_swap_b32_e32 v128, v129
	s_and_saveexec_b64 s[16:17], s[14:15]
	s_cbranch_execz .LBB0_382

.LBB0_425:
	v_lshl_or_b32 v200, s48, 8, v250
	v_lshl_add_u32 v230, s22, 8, v248
	v_ashrrev_i32_e32 v201, 31, v200
	v_lshlrev_b64 v[238:239], 1, v[200:201]
	v_ashrrev_i32_e32 v231, 31, v230
	v_lshl_add_u64 v[80:81], s[64:65], 0, v[238:239]
	v_lshlrev_b64 v[186:187], 11, v[230:231]
	v_lshl_add_u64 v[82:83], v[80:81], 0, v[186:187]
	global_load_dwordx4 v[232:235], v[82:83], off
	global_load_dwordx4 v[244:247], v[82:83], off offset:256
	v_or_b32_e32 v226, 16, v230
	v_ashrrev_i32_e32 v227, 31, v226
	v_or_b32_e32 v222, 32, v230
	v_lshlrev_b64 v[228:229], 11, v[226:227]
	v_ashrrev_i32_e32 v223, 31, v222
	v_or_b32_e32 v218, 48, v230
	v_lshl_add_u64 v[82:83], v[80:81], 0, v[228:229]
	v_lshlrev_b64 v[224:225], 11, v[222:223]
	v_ashrrev_i32_e32 v219, 31, v218
	v_add_u32_e32 v214, 0x80, v230
	global_load_dwordx4 v[164:167], v[82:83], off
	global_load_dwordx4 v[160:163], v[82:83], off offset:256
	v_lshl_add_u64 v[82:83], v[80:81], 0, v[224:225]
	v_lshlrev_b64 v[220:221], 11, v[218:219]
	v_ashrrev_i32_e32 v215, 31, v214
	v_add_u32_e32 v210, 0x90, v230
	global_load_dwordx4 v[156:159], v[82:83], off
	global_load_dwordx4 v[152:155], v[82:83], off offset:256
	v_lshl_add_u64 v[82:83], v[80:81], 0, v[220:221]
	v_lshlrev_b64 v[216:217], 11, v[214:215]
	v_ashrrev_i32_e32 v211, 31, v210
	v_add_u32_e32 v206, 0xa0, v230
	v_add_u32_e32 v202, 0xb0, v230
	global_load_dwordx4 v[148:151], v[82:83], off
	global_load_dwordx4 v[144:147], v[82:83], off offset:256
	v_lshl_add_u64 v[82:83], v[80:81], 0, v[216:217]
	v_lshlrev_b64 v[212:213], 11, v[210:211]
	v_ashrrev_i32_e32 v207, 31, v206
	v_ashrrev_i32_e32 v203, 31, v202
	global_load_dwordx4 v[140:143], v[82:83], off
	global_load_dwordx4 v[136:139], v[82:83], off offset:256
	v_lshl_add_u64 v[82:83], v[80:81], 0, v[212:213]
	v_lshlrev_b64 v[208:209], 11, v[206:207]
	v_lshlrev_b64 v[204:205], 11, v[202:203]
	global_load_dwordx4 v[132:135], v[82:83], off
	global_load_dwordx4 v[124:127], v[82:83], off offset:256
	v_lshl_add_u64 v[82:83], v[80:81], 0, v[208:209]
	v_lshl_add_u64 v[80:81], v[80:81], 0, v[204:205]
	global_load_dwordx4 v[108:111], v[82:83], off
	global_load_dwordx4 v[104:107], v[82:83], off offset:256
	global_load_dwordx4 v[84:87], v[80:81], off
	s_nop 0
	global_load_dwordx4 v[80:83], v[80:81], off offset:256
	s_waitcnt vmcnt(0)
	v_lshlrev_b32_e32 v236, 16, v232
	v_and_b32_e32 v237, 0xffff0000, v232
	v_lshlrev_b32_e32 v188, 16, v234
	v_and_b32_e32 v189, 0xffff0000, v234
	v_lshlrev_b32_e32 v234, 16, v235
	v_and_b32_e32 v235, 0xffff0000, v235
	v_lshlrev_b32_e32 v232, 16, v233
	v_and_b32_e32 v233, 0xffff0000, v233
	v_pk_add_f32 v[236:237], v[180:181], v[236:237]
	v_pk_add_f32 v[180:181], v[178:179], v[234:235]
	v_lshlrev_b32_e32 v178, 16, v245
	v_and_b32_e32 v179, 0xffff0000, v245
	v_pk_add_f32 v[232:233], v[182:183], v[232:233]
	v_pk_add_f32 v[182:183], v[176:177], v[188:189]
	v_pk_add_f32 v[174:175], v[174:175], v[178:179]
	v_lshl_add_u64 v[178:179], s[64:65], 0, v[186:187]
	v_mov_b32_e32 v186, 0
	v_mov_b32_e32 v187, 0
	v_cvt_pk_fp8_f32 v186, v236, v237
	v_cvt_pk_fp8_f32 v187, v182, v183
	v_lshlrev_b32_e32 v176, 16, v244
	v_and_b32_e32 v177, 0xffff0000, v244
	v_cvt_pk_fp8_f32 v186, v232, v233 op_sel:[0,0,1]
	v_cvt_pk_fp8_f32 v187, v180, v181 op_sel:[0,0,1]
	v_lshlrev_b32_e32 v188, 16, v246
	v_and_b32_e32 v189, 0xffff0000, v246
	v_pk_add_f32 v[172:173], v[172:173], v[176:177]
	v_lshlrev_b64 v[176:177], 10, v[230:231]
	v_lshlrev_b32_e32 v234, 16, v247
	v_and_b32_e32 v235, 0xffff0000, v247
	v_pk_add_f32 v[168:169], v[168:169], v[188:189]
	v_lshl_add_u64 v[188:189], s[54:55], 0, v[176:177]
	v_pk_add_f32 v[170:171], v[170:171], v[234:235]
	v_lshl_add_u64 v[234:235], v[178:179], 0, v[238:239]
	v_lshl_add_u64 v[188:189], v[188:189], 0, v[200:201]
	v_cvt_pk_bf16_f32 v244, v236, v237
	v_cvt_pk_bf16_f32 v245, v232, v233
	v_cvt_pk_bf16_f32 v246, v182, v183
	v_cvt_pk_bf16_f32 v247, v180, v181
	global_store_dwordx4 v[234:235], v[244:247], off
	global_store_dwordx2 v[188:189], v[186:187], off
	v_mul_f32_e32 v186, v237, v237
	v_mul_f32_e32 v187, v233, v233
	v_fmac_f32_e32 v186, v236, v236
	v_fmac_f32_e32 v187, v232, v232
	v_mul_f32_e32 v183, v183, v183
	v_add_f32_e32 v186, v186, v187
	v_fmac_f32_e32 v183, v182, v182
	v_mul_f32_e32 v181, v181, v181
	v_add_f32_e32 v182, v183, v186
	v_fmac_f32_e32 v181, v180, v180
	v_cvt_pk_bf16_f32 v180, v172, v173
	v_add_f32_e32 v186, v181, v182
	v_cvt_pk_bf16_f32 v181, v174, v175
	v_cvt_pk_bf16_f32 v182, v168, v169
	v_cvt_pk_bf16_f32 v183, v170, v171
	global_store_dwordx4 v[234:235], v[180:183], off offset:256
	v_sub_co_u32_e32 v176, vcc, 0, v176
	s_nop 0
	v_mov_b32_e32 v180, 0
	v_cvt_pk_fp8_f32 v180, v172, v173
	v_mul_f32_e32 v173, v173, v173
	v_mov_b32_e32 v181, 0
	v_fmac_f32_e32 v173, v172, v172
	v_mul_f32_e32 v172, v175, v175
	v_cvt_pk_fp8_f32 v181, v168, v169
	v_fmac_f32_e32 v172, v174, v174
	v_mul_f32_e32 v169, v169, v169
	v_subb_co_u32_e32 v177, vcc, 0, v177, vcc
	v_add_f32_e32 v172, v173, v172
	v_fmac_f32_e32 v169, v168, v168
	v_lshl_add_u64 v[176:177], v[178:179], 0, v[176:177]
	v_add_f32_e32 v168, v169, v172
	v_mul_f32_e32 v169, v171, v171
	v_lshl_add_u64 v[176:177], v[176:177], 0, v[200:201]
	v_fmac_f32_e32 v169, v170, v170
	v_cvt_pk_fp8_f32 v181, v170, v171 op_sel:[0,0,1]
	v_add_co_u32_e32 v176, vcc, s21, v176
	v_add_f32_e32 v168, v169, v168
	v_and_b32_e32 v170, 64, v243
	v_addc_co_u32_e32 v177, vcc, 0, v177, vcc
	v_add_f32_e32 v169, v186, v168
	v_xor_b32_e32 v168, 16, v243
	v_add_u32_e32 v171, 64, v170
	v_cmp_lt_i32_e32 vcc, v168, v171
	v_cvt_pk_fp8_f32 v180, v174, v175 op_sel:[0,0,1]
	global_store_dwordx2 v[176:177], v[180:181], off offset:128
	v_cndmask_b32_e32 v168, v243, v168, vcc
	v_lshlrev_b32_e32 v168, 2, v168
	v_mov_b32_e32 v170, v169
	s_nop 1
	v_permlane16_swap_b32_e32 v169, v170
	s_waitcnt lgkmcnt(0)
	v_add_f32_e32 v170, v169, v170
	v_xor_b32_e32 v169, 32, v243
	v_cmp_lt_i32_e32 vcc, v169, v171
	s_nop 1
	v_cndmask_b32_e32 v169, v243, v169, vcc
	v_lshlrev_b32_e32 v169, 2, v169
	v_mov_b32_e32 v171, v170
	s_nop 1
	v_permlane32_swap_b32_e32 v170, v171
	s_and_saveexec_b64 s[14:15], s[36:37]
	s_cbranch_execz .LBB0_427
	s_waitcnt lgkmcnt(0)
	v_add_f32_e32 v170, v170, v171
	v_fma_f32 v170, v170, s18, 0.5
	v_cvt_u32_f32_e32 v172, v170
	v_readlane_b32 s16, v253, 5
	v_readlane_b32 s17, v253, 6
	s_nop 1
	v_lshl_add_u64 v[170:171], v[230:231], 2, s[16:17]
	global_atomic_add v[170:171], v172, off
.LBB0_427:
	s_or_b64 exec, exec, s[14:15]
	v_lshlrev_b32_e32 v170, 16, v164
	s_waitcnt lgkmcnt(0)
	v_and_b32_e32 v171, 0xffff0000, v164
	v_lshlrev_b32_e32 v164, 16, v165
	v_and_b32_e32 v165, 0xffff0000, v165
	v_lshlrev_b32_e32 v172, 16, v166
	v_and_b32_e32 v173, 0xffff0000, v166
	v_lshlrev_b32_e32 v166, 16, v167
	v_and_b32_e32 v167, 0xffff0000, v167
	v_pk_add_f32 v[130:131], v[130:131], v[164:165]
	v_pk_add_f32 v[122:123], v[122:123], v[166:167]
	v_lshlrev_b32_e32 v164, 16, v160
	v_and_b32_e32 v165, 0xffff0000, v160
	v_lshlrev_b32_e32 v160, 16, v161
	v_and_b32_e32 v161, 0xffff0000, v161
	v_lshlrev_b32_e32 v166, 16, v162
	v_and_b32_e32 v167, 0xffff0000, v162
	v_lshlrev_b32_e32 v162, 16, v163
	v_and_b32_e32 v163, 0xffff0000, v163
	v_pk_add_f32 v[128:129], v[128:129], v[170:171]
	v_pk_add_f32 v[120:121], v[120:121], v[172:173]
	v_pk_add_f32 v[118:119], v[118:119], v[160:161]
	v_pk_add_f32 v[160:161], v[114:115], v[162:163]
	v_pk_add_f32 v[162:163], v[112:113], v[166:167]
	v_mov_b32_e32 v166, 0
	v_mov_b32_e32 v167, 0
	v_cvt_pk_fp8_f32 v166, v128, v129
	v_cvt_pk_fp8_f32 v167, v120, v121
	v_lshl_add_u64 v[170:171], s[64:65], 0, v[228:229]
	v_pk_add_f32 v[116:117], v[116:117], v[164:165]
	v_cvt_pk_fp8_f32 v166, v130, v131 op_sel:[0,0,1]
	v_cvt_pk_fp8_f32 v167, v122, v123 op_sel:[0,0,1]
	v_lshlrev_b64 v[164:165], 10, v[226:227]
	v_cvt_pk_bf16_f32 v112, v128, v129
	v_cvt_pk_bf16_f32 v113, v130, v131
	v_lshl_add_u64 v[172:173], v[200:201], 1, v[170:171]
	v_cvt_pk_bf16_f32 v114, v120, v121
	v_cvt_pk_bf16_f32 v115, v122, v123
	global_store_dwordx4 v[172:173], v[112:115], off
	s_nop 1
	v_lshl_add_u64 v[112:113], s[54:55], 0, v[164:165]
	v_lshl_add_u64 v[112:113], v[112:113], 0, v[200:201]
	global_store_dwordx2 v[112:113], v[166:167], off
	v_mul_f32_e32 v112, v129, v129
	v_mul_f32_e32 v113, v131, v131
	v_fmac_f32_e32 v112, v128, v128
	v_fmac_f32_e32 v113, v130, v130
	v_add_f32_e32 v112, v112, v113
	v_mul_f32_e32 v113, v121, v121
	v_fmac_f32_e32 v113, v120, v120
	v_add_f32_e32 v112, v113, v112
	v_mul_f32_e32 v113, v123, v123
	v_fmac_f32_e32 v113, v122, v122
	v_add_f32_e32 v122, v113, v112
	v_cvt_pk_bf16_f32 v112, v116, v117
	v_cvt_pk_bf16_f32 v113, v118, v119
	v_cvt_pk_bf16_f32 v114, v162, v163
	v_cvt_pk_bf16_f32 v115, v160, v161
	global_store_dwordx4 v[172:173], v[112:115], off offset:256
	v_mov_b32_e32 v120, 0
	v_cvt_pk_fp8_f32 v120, v116, v117
	v_mul_f32_e32 v112, v117, v117
	v_mul_f32_e32 v113, v119, v119
	v_fmac_f32_e32 v112, v116, v116
	v_fmac_f32_e32 v113, v118, v118
	v_add_f32_e32 v112, v112, v113
	v_mul_f32_e32 v113, v163, v163
	v_fmac_f32_e32 v113, v162, v162
	v_add_f32_e32 v112, v113, v112
	v_mul_f32_e32 v113, v161, v161
	v_fmac_f32_e32 v113, v160, v160
	v_add_f32_e32 v112, v113, v112
	v_add_f32_e32 v116, v122, v112
	v_mov_b32_e32 v117, v116
	s_nop 1
	v_permlane16_swap_b32_e32 v116, v117
	v_mov_b32_e32 v121, 0
	v_sub_co_u32_e32 v112, vcc, 0, v164
	v_cvt_pk_fp8_f32 v121, v162, v163
	s_nop 0
	v_subb_co_u32_e32 v113, vcc, 0, v165, vcc
	v_lshl_add_u64 v[112:113], v[170:171], 0, v[112:113]
	v_lshl_add_u64 v[114:115], v[112:113], 0, v[200:201]
	s_waitcnt lgkmcnt(0)
	v_add_f32_e32 v112, v116, v117
	v_mov_b32_e32 v113, v112
	s_nop 1
	v_permlane32_swap_b32_e32 v112, v113
	v_cvt_pk_fp8_f32 v120, v118, v119 op_sel:[0,0,1]
	v_cvt_pk_fp8_f32 v121, v160, v161 op_sel:[0,0,1]
	v_add_co_u32_e32 v114, vcc, s21, v114
	s_nop 1
	v_addc_co_u32_e32 v115, vcc, 0, v115, vcc
	global_store_dwordx2 v[114:115], v[120:121], off offset:128
	s_and_saveexec_b64 s[14:15], s[36:37]
	s_cbranch_execz .LBB0_429
	s_waitcnt lgkmcnt(0)
	v_add_f32_e32 v112, v112, v113
	v_fma_f32 v112, v112, s18, 0.5
	v_cvt_u32_f32_e32 v114, v112
	v_readlane_b32 s16, v253, 5
	v_readlane_b32 s17, v253, 6
	s_nop 1
	v_lshl_add_u64 v[112:113], v[226:227], 2, s[16:17]
	global_atomic_add v[112:113], v114, off
.LBB0_429:
	s_or_b64 exec, exec, s[14:15]
	v_lshlrev_b32_e32 v112, 16, v156
	s_waitcnt lgkmcnt(0)
	v_and_b32_e32 v113, 0xffff0000, v156
	v_lshlrev_b32_e32 v118, 16, v159
	v_and_b32_e32 v119, 0xffff0000, v159
	v_lshlrev_b32_e32 v116, 16, v158
	v_and_b32_e32 v117, 0xffff0000, v158
	v_pk_add_f32 v[100:101], v[100:101], v[112:113]
	v_pk_add_f32 v[98:99], v[98:99], v[118:119]
	v_lshlrev_b32_e32 v112, 16, v152
	v_and_b32_e32 v113, 0xffff0000, v152
	v_lshlrev_b32_e32 v118, 16, v155
	v_and_b32_e32 v119, 0xffff0000, v155
	v_pk_add_f32 v[96:97], v[96:97], v[116:117]
	v_pk_add_f32 v[92:93], v[92:93], v[112:113]
	v_pk_add_f32 v[112:113], v[90:91], v[118:119]
	v_mov_b32_e32 v118, 0
	v_mov_b32_e32 v119, 0
	v_cvt_pk_fp8_f32 v118, v100, v101
	v_cvt_pk_fp8_f32 v119, v96, v97
	v_lshlrev_b32_e32 v114, 16, v157
	v_and_b32_e32 v115, 0xffff0000, v157
	v_pk_add_f32 v[102:103], v[102:103], v[114:115]
	v_lshlrev_b32_e32 v114, 16, v153
	v_and_b32_e32 v115, 0xffff0000, v153
	v_lshlrev_b32_e32 v116, 16, v154
	v_and_b32_e32 v117, 0xffff0000, v154
	v_lshl_add_u64 v[120:121], s[64:65], 0, v[224:225]
	v_cvt_pk_fp8_f32 v118, v102, v103 op_sel:[0,0,1]
	v_cvt_pk_fp8_f32 v119, v98, v99 op_sel:[0,0,1]
	v_pk_add_f32 v[94:95], v[94:95], v[114:115]
	v_pk_add_f32 v[114:115], v[88:89], v[116:117]
	v_lshlrev_b64 v[116:117], 10, v[222:223]
	v_cvt_pk_bf16_f32 v88, v100, v101
	v_cvt_pk_bf16_f32 v89, v102, v103
	v_lshl_add_u64 v[122:123], v[200:201], 1, v[120:121]
	v_cvt_pk_bf16_f32 v90, v96, v97
	v_cvt_pk_bf16_f32 v91, v98, v99
	global_store_dwordx4 v[122:123], v[88:91], off
	s_nop 1
	v_lshl_add_u64 v[88:89], s[54:55], 0, v[116:117]
	v_lshl_add_u64 v[88:89], v[88:89], 0, v[200:201]
	global_store_dwordx2 v[88:89], v[118:119], off
	v_mul_f32_e32 v88, v101, v101
	v_mul_f32_e32 v89, v103, v103
	v_fmac_f32_e32 v88, v100, v100
	v_fmac_f32_e32 v89, v102, v102
	v_add_f32_e32 v88, v88, v89
	v_mul_f32_e32 v89, v97, v97
	v_fmac_f32_e32 v89, v96, v96
	v_add_f32_e32 v88, v89, v88
	v_mul_f32_e32 v89, v99, v99
	v_fmac_f32_e32 v89, v98, v98
	v_add_f32_e32 v98, v89, v88
	v_cvt_pk_bf16_f32 v88, v92, v93
	v_cvt_pk_bf16_f32 v89, v94, v95
	v_cvt_pk_bf16_f32 v90, v114, v115
	v_cvt_pk_bf16_f32 v91, v112, v113
	global_store_dwordx4 v[122:123], v[88:91], off offset:256
	v_mov_b32_e32 v96, 0
	v_cvt_pk_fp8_f32 v96, v92, v93
	v_mul_f32_e32 v88, v93, v93
	v_mul_f32_e32 v89, v95, v95
	v_fmac_f32_e32 v88, v92, v92
	v_fmac_f32_e32 v89, v94, v94
	v_add_f32_e32 v88, v88, v89
	v_mul_f32_e32 v89, v115, v115
	v_fmac_f32_e32 v89, v114, v114
	v_add_f32_e32 v88, v89, v88
	v_mul_f32_e32 v89, v113, v113
	v_fmac_f32_e32 v89, v112, v112
	v_add_f32_e32 v88, v89, v88
	v_add_f32_e32 v92, v98, v88
	v_mov_b32_e32 v93, v92
	s_nop 1
	v_permlane16_swap_b32_e32 v92, v93
	v_mov_b32_e32 v97, 0
	v_sub_co_u32_e32 v88, vcc, 0, v116
	v_cvt_pk_fp8_f32 v97, v114, v115
	s_nop 0
	v_subb_co_u32_e32 v89, vcc, 0, v117, vcc
	v_lshl_add_u64 v[88:89], v[120:121], 0, v[88:89]
	v_lshl_add_u64 v[90:91], v[88:89], 0, v[200:201]
	s_waitcnt lgkmcnt(0)
	v_add_f32_e32 v88, v92, v93
	v_mov_b32_e32 v89, v88
	s_nop 1
	v_permlane32_swap_b32_e32 v88, v89
	v_cvt_pk_fp8_f32 v96, v94, v95 op_sel:[0,0,1]
	v_cvt_pk_fp8_f32 v97, v112, v113 op_sel:[0,0,1]
	v_add_co_u32_e32 v90, vcc, s21, v90
	s_nop 1
	v_addc_co_u32_e32 v91, vcc, 0, v91, vcc
	global_store_dwordx2 v[90:91], v[96:97], off offset:128
	s_and_saveexec_b64 s[14:15], s[36:37]
	s_cbranch_execz .LBB0_431
	s_waitcnt lgkmcnt(0)
	v_add_f32_e32 v88, v88, v89
	v_fma_f32 v88, v88, s18, 0.5
	v_cvt_u32_f32_e32 v90, v88
	v_readlane_b32 s16, v253, 5
	v_readlane_b32 s17, v253, 6
	s_nop 1
	v_lshl_add_u64 v[88:89], v[222:223], 2, s[16:17]
	global_atomic_add v[88:89], v90, off
.LBB0_431:
	s_or_b64 exec, exec, s[14:15]
	v_lshlrev_b32_e32 v88, 16, v148
	s_waitcnt lgkmcnt(0)
	v_and_b32_e32 v89, 0xffff0000, v148
	v_lshlrev_b32_e32 v94, 16, v151
	v_and_b32_e32 v95, 0xffff0000, v151
	v_lshlrev_b32_e32 v92, 16, v150
	v_and_b32_e32 v93, 0xffff0000, v150
	v_pk_add_f32 v[76:77], v[76:77], v[88:89]
	v_pk_add_f32 v[74:75], v[74:75], v[94:95]
	v_lshlrev_b32_e32 v88, 16, v144
	v_and_b32_e32 v89, 0xffff0000, v144
	v_lshlrev_b32_e32 v94, 16, v147
	v_and_b32_e32 v95, 0xffff0000, v147
	v_pk_add_f32 v[72:73], v[72:73], v[92:93]
	v_pk_add_f32 v[68:69], v[68:69], v[88:89]
	v_pk_add_f32 v[88:89], v[66:67], v[94:95]
	v_mov_b32_e32 v94, 0
	v_mov_b32_e32 v95, 0
	v_cvt_pk_fp8_f32 v94, v76, v77
	v_cvt_pk_fp8_f32 v95, v72, v73
	v_lshlrev_b32_e32 v90, 16, v149
	v_and_b32_e32 v91, 0xffff0000, v149
	v_pk_add_f32 v[78:79], v[78:79], v[90:91]
	v_lshlrev_b32_e32 v90, 16, v145
	v_and_b32_e32 v91, 0xffff0000, v145
	v_lshlrev_b32_e32 v92, 16, v146
	v_and_b32_e32 v93, 0xffff0000, v146
	v_lshl_add_u64 v[96:97], s[64:65], 0, v[220:221]
	v_cvt_pk_fp8_f32 v94, v78, v79 op_sel:[0,0,1]
	v_cvt_pk_fp8_f32 v95, v74, v75 op_sel:[0,0,1]
	v_pk_add_f32 v[70:71], v[70:71], v[90:91]
	v_pk_add_f32 v[90:91], v[64:65], v[92:93]
	v_lshlrev_b64 v[92:93], 10, v[218:219]
	v_cvt_pk_bf16_f32 v64, v76, v77
	v_cvt_pk_bf16_f32 v65, v78, v79
	v_lshl_add_u64 v[98:99], v[200:201], 1, v[96:97]
	v_cvt_pk_bf16_f32 v66, v72, v73
	v_cvt_pk_bf16_f32 v67, v74, v75
	global_store_dwordx4 v[98:99], v[64:67], off
	s_nop 1
	v_lshl_add_u64 v[64:65], s[54:55], 0, v[92:93]
	v_lshl_add_u64 v[64:65], v[64:65], 0, v[200:201]
	global_store_dwordx2 v[64:65], v[94:95], off
	v_mul_f32_e32 v64, v77, v77
	v_mul_f32_e32 v65, v79, v79
	v_fmac_f32_e32 v64, v76, v76
	v_fmac_f32_e32 v65, v78, v78
	v_add_f32_e32 v64, v64, v65
	v_mul_f32_e32 v65, v73, v73
	v_fmac_f32_e32 v65, v72, v72
	v_add_f32_e32 v64, v65, v64
	v_mul_f32_e32 v65, v75, v75
	v_fmac_f32_e32 v65, v74, v74
	v_add_f32_e32 v74, v65, v64
	v_cvt_pk_bf16_f32 v64, v68, v69
	v_cvt_pk_bf16_f32 v65, v70, v71
	v_cvt_pk_bf16_f32 v66, v90, v91
	v_cvt_pk_bf16_f32 v67, v88, v89
	global_store_dwordx4 v[98:99], v[64:67], off offset:256
	v_mov_b32_e32 v72, 0
	v_cvt_pk_fp8_f32 v72, v68, v69
	v_mul_f32_e32 v64, v69, v69
	v_mul_f32_e32 v65, v71, v71
	v_fmac_f32_e32 v64, v68, v68
	v_fmac_f32_e32 v65, v70, v70
	v_add_f32_e32 v64, v64, v65
	v_mul_f32_e32 v65, v91, v91
	v_fmac_f32_e32 v65, v90, v90
	v_add_f32_e32 v64, v65, v64
	v_mul_f32_e32 v65, v89, v89
	v_fmac_f32_e32 v65, v88, v88
	v_add_f32_e32 v64, v65, v64
	v_add_f32_e32 v68, v74, v64
	v_mov_b32_e32 v69, v68
	s_nop 1
	v_permlane16_swap_b32_e32 v68, v69
	v_mov_b32_e32 v73, 0
	v_sub_co_u32_e32 v64, vcc, 0, v92
	v_cvt_pk_fp8_f32 v73, v90, v91
	s_nop 0
	v_subb_co_u32_e32 v65, vcc, 0, v93, vcc
	v_lshl_add_u64 v[64:65], v[96:97], 0, v[64:65]
	v_lshl_add_u64 v[66:67], v[64:65], 0, v[200:201]
	s_waitcnt lgkmcnt(0)
	v_add_f32_e32 v64, v68, v69
	v_mov_b32_e32 v65, v64
	s_nop 1
	v_permlane32_swap_b32_e32 v64, v65
	v_cvt_pk_fp8_f32 v72, v70, v71 op_sel:[0,0,1]
	v_cvt_pk_fp8_f32 v73, v88, v89 op_sel:[0,0,1]
	v_add_co_u32_e32 v66, vcc, s21, v66
	s_nop 1
	v_addc_co_u32_e32 v67, vcc, 0, v67, vcc
	global_store_dwordx2 v[66:67], v[72:73], off offset:128
	s_and_saveexec_b64 s[14:15], s[36:37]
	s_cbranch_execz .LBB0_433
	s_waitcnt lgkmcnt(0)
	v_add_f32_e32 v64, v64, v65
	v_fma_f32 v64, v64, s18, 0.5
	v_cvt_u32_f32_e32 v66, v64
	v_readlane_b32 s16, v253, 5
	v_readlane_b32 s17, v253, 6
	s_nop 1
	v_lshl_add_u64 v[64:65], v[218:219], 2, s[16:17]
	global_atomic_add v[64:65], v66, off
.LBB0_433:
	s_or_b64 exec, exec, s[14:15]
	v_lshlrev_b32_e32 v64, 16, v140
	s_waitcnt lgkmcnt(0)
	v_and_b32_e32 v65, 0xffff0000, v140
	v_lshlrev_b32_e32 v70, 16, v143
	v_and_b32_e32 v71, 0xffff0000, v143
	v_lshlrev_b32_e32 v68, 16, v142
	v_and_b32_e32 v69, 0xffff0000, v142
	v_pk_add_f32 v[60:61], v[60:61], v[64:65]
	v_pk_add_f32 v[58:59], v[58:59], v[70:71]
	v_lshlrev_b32_e32 v64, 16, v136
	v_and_b32_e32 v65, 0xffff0000, v136
	v_lshlrev_b32_e32 v70, 16, v139
	v_and_b32_e32 v71, 0xffff0000, v139
	v_pk_add_f32 v[56:57], v[56:57], v[68:69]
	v_pk_add_f32 v[52:53], v[52:53], v[64:65]
	v_pk_add_f32 v[64:65], v[50:51], v[70:71]
	v_mov_b32_e32 v70, 0
	v_mov_b32_e32 v71, 0
	v_cvt_pk_fp8_f32 v70, v60, v61
	v_cvt_pk_fp8_f32 v71, v56, v57
	v_lshlrev_b32_e32 v66, 16, v141
	v_and_b32_e32 v67, 0xffff0000, v141
	v_pk_add_f32 v[62:63], v[62:63], v[66:67]
	v_lshlrev_b32_e32 v66, 16, v137
	v_and_b32_e32 v67, 0xffff0000, v137
	v_lshlrev_b32_e32 v68, 16, v138
	v_and_b32_e32 v69, 0xffff0000, v138
	v_lshl_add_u64 v[72:73], s[64:65], 0, v[216:217]
	v_cvt_pk_fp8_f32 v70, v62, v63 op_sel:[0,0,1]
	v_cvt_pk_fp8_f32 v71, v58, v59 op_sel:[0,0,1]
	v_pk_add_f32 v[54:55], v[54:55], v[66:67]
	v_pk_add_f32 v[66:67], v[48:49], v[68:69]
	v_lshlrev_b64 v[68:69], 10, v[214:215]
	v_cvt_pk_bf16_f32 v48, v60, v61
	v_cvt_pk_bf16_f32 v49, v62, v63
	v_lshl_add_u64 v[74:75], v[200:201], 1, v[72:73]
	v_cvt_pk_bf16_f32 v50, v56, v57
	v_cvt_pk_bf16_f32 v51, v58, v59
	global_store_dwordx4 v[74:75], v[48:51], off
	s_nop 1
	v_lshl_add_u64 v[48:49], s[54:55], 0, v[68:69]
	v_lshl_add_u64 v[48:49], v[48:49], 0, v[200:201]
	global_store_dwordx2 v[48:49], v[70:71], off
	v_mul_f32_e32 v48, v61, v61
	v_mul_f32_e32 v49, v63, v63
	v_fmac_f32_e32 v48, v60, v60
	v_fmac_f32_e32 v49, v62, v62
	v_add_f32_e32 v48, v48, v49
	v_mul_f32_e32 v49, v57, v57
	v_fmac_f32_e32 v49, v56, v56
	v_add_f32_e32 v48, v49, v48
	v_mul_f32_e32 v49, v59, v59
	v_fmac_f32_e32 v49, v58, v58
	v_add_f32_e32 v58, v49, v48
	v_cvt_pk_bf16_f32 v48, v52, v53
	v_cvt_pk_bf16_f32 v49, v54, v55
	v_cvt_pk_bf16_f32 v50, v66, v67
	v_cvt_pk_bf16_f32 v51, v64, v65
	global_store_dwordx4 v[74:75], v[48:51], off offset:256
	v_mov_b32_e32 v56, 0
	v_cvt_pk_fp8_f32 v56, v52, v53
	v_mul_f32_e32 v48, v53, v53
	v_mul_f32_e32 v49, v55, v55
	v_fmac_f32_e32 v48, v52, v52
	v_fmac_f32_e32 v49, v54, v54
	v_add_f32_e32 v48, v48, v49
	v_mul_f32_e32 v49, v67, v67
	v_fmac_f32_e32 v49, v66, v66
	v_add_f32_e32 v48, v49, v48
	v_mul_f32_e32 v49, v65, v65
	v_fmac_f32_e32 v49, v64, v64
	v_add_f32_e32 v48, v49, v48
	v_add_f32_e32 v52, v58, v48
	v_mov_b32_e32 v53, v52
	s_nop 1
	v_permlane16_swap_b32_e32 v52, v53
	v_mov_b32_e32 v57, 0
	v_sub_co_u32_e32 v48, vcc, 0, v68
	v_cvt_pk_fp8_f32 v57, v66, v67
	s_nop 0
	v_subb_co_u32_e32 v49, vcc, 0, v69, vcc
	v_lshl_add_u64 v[48:49], v[72:73], 0, v[48:49]
	v_lshl_add_u64 v[50:51], v[48:49], 0, v[200:201]
	s_waitcnt lgkmcnt(0)
	v_add_f32_e32 v48, v52, v53
	v_mov_b32_e32 v49, v48
	s_nop 1
	v_permlane32_swap_b32_e32 v48, v49
	v_cvt_pk_fp8_f32 v56, v54, v55 op_sel:[0,0,1]
	v_cvt_pk_fp8_f32 v57, v64, v65 op_sel:[0,0,1]
	v_add_co_u32_e32 v50, vcc, s21, v50
	s_nop 1
	v_addc_co_u32_e32 v51, vcc, 0, v51, vcc
	global_store_dwordx2 v[50:51], v[56:57], off offset:128
	s_and_saveexec_b64 s[14:15], s[36:37]
	s_cbranch_execz .LBB0_435
	s_waitcnt lgkmcnt(0)
	v_add_f32_e32 v48, v48, v49
	v_fma_f32 v48, v48, s18, 0.5
	v_cvt_u32_f32_e32 v50, v48
	v_readlane_b32 s16, v253, 5
	v_readlane_b32 s17, v253, 6
	s_nop 1
	v_lshl_add_u64 v[48:49], v[214:215], 2, s[16:17]
	global_atomic_add v[48:49], v50, off
.LBB0_435:
	s_or_b64 exec, exec, s[14:15]
	v_lshlrev_b32_e32 v48, 16, v132
	s_waitcnt lgkmcnt(0)
	v_and_b32_e32 v49, 0xffff0000, v132
	v_lshlrev_b32_e32 v54, 16, v135
	v_and_b32_e32 v55, 0xffff0000, v135
	v_lshlrev_b32_e32 v52, 16, v134
	v_and_b32_e32 v53, 0xffff0000, v134
	v_pk_add_f32 v[44:45], v[44:45], v[48:49]
	v_pk_add_f32 v[42:43], v[42:43], v[54:55]
	v_lshlrev_b32_e32 v48, 16, v124
	v_and_b32_e32 v49, 0xffff0000, v124
	v_lshlrev_b32_e32 v54, 16, v127
	v_and_b32_e32 v55, 0xffff0000, v127
	v_pk_add_f32 v[40:41], v[40:41], v[52:53]
	v_pk_add_f32 v[36:37], v[36:37], v[48:49]
	v_pk_add_f32 v[48:49], v[34:35], v[54:55]
	v_mov_b32_e32 v54, 0
	v_mov_b32_e32 v55, 0
	v_cvt_pk_fp8_f32 v54, v44, v45
	v_cvt_pk_fp8_f32 v55, v40, v41
	v_lshlrev_b32_e32 v50, 16, v133
	v_and_b32_e32 v51, 0xffff0000, v133
	v_pk_add_f32 v[46:47], v[46:47], v[50:51]
	v_lshlrev_b32_e32 v50, 16, v125
	v_and_b32_e32 v51, 0xffff0000, v125
	v_lshlrev_b32_e32 v52, 16, v126
	v_and_b32_e32 v53, 0xffff0000, v126
	v_lshl_add_u64 v[56:57], s[64:65], 0, v[212:213]
	v_cvt_pk_fp8_f32 v54, v46, v47 op_sel:[0,0,1]
	v_cvt_pk_fp8_f32 v55, v42, v43 op_sel:[0,0,1]
	v_pk_add_f32 v[38:39], v[38:39], v[50:51]
	v_pk_add_f32 v[50:51], v[32:33], v[52:53]
	v_lshlrev_b64 v[52:53], 10, v[210:211]
	v_cvt_pk_bf16_f32 v32, v44, v45
	v_cvt_pk_bf16_f32 v33, v46, v47
	v_lshl_add_u64 v[58:59], v[200:201], 1, v[56:57]
	v_cvt_pk_bf16_f32 v34, v40, v41
	v_cvt_pk_bf16_f32 v35, v42, v43
	global_store_dwordx4 v[58:59], v[32:35], off
	s_nop 1
	v_lshl_add_u64 v[32:33], s[54:55], 0, v[52:53]
	v_lshl_add_u64 v[32:33], v[32:33], 0, v[200:201]
	global_store_dwordx2 v[32:33], v[54:55], off
	v_mul_f32_e32 v32, v45, v45
	v_mul_f32_e32 v33, v47, v47
	v_fmac_f32_e32 v32, v44, v44
	v_fmac_f32_e32 v33, v46, v46
	v_add_f32_e32 v32, v32, v33
	v_mul_f32_e32 v33, v41, v41
	v_fmac_f32_e32 v33, v40, v40
	v_add_f32_e32 v32, v33, v32
	v_mul_f32_e32 v33, v43, v43
	v_fmac_f32_e32 v33, v42, v42
	v_add_f32_e32 v42, v33, v32
	v_cvt_pk_bf16_f32 v32, v36, v37
	v_cvt_pk_bf16_f32 v33, v38, v39
	v_cvt_pk_bf16_f32 v34, v50, v51
	v_cvt_pk_bf16_f32 v35, v48, v49
	global_store_dwordx4 v[58:59], v[32:35], off offset:256
	v_mov_b32_e32 v40, 0
	v_cvt_pk_fp8_f32 v40, v36, v37
	v_mul_f32_e32 v32, v37, v37
	v_mul_f32_e32 v33, v39, v39
	v_fmac_f32_e32 v32, v36, v36
	v_fmac_f32_e32 v33, v38, v38
	v_add_f32_e32 v32, v32, v33
	v_mul_f32_e32 v33, v51, v51
	v_fmac_f32_e32 v33, v50, v50
	v_add_f32_e32 v32, v33, v32
	v_mul_f32_e32 v33, v49, v49
	v_fmac_f32_e32 v33, v48, v48
	v_add_f32_e32 v32, v33, v32
	v_add_f32_e32 v36, v42, v32
	v_mov_b32_e32 v37, v36
	s_nop 1
	v_permlane16_swap_b32_e32 v36, v37
	v_mov_b32_e32 v41, 0
	v_sub_co_u32_e32 v32, vcc, 0, v52
	v_cvt_pk_fp8_f32 v41, v50, v51
	s_nop 0
	v_subb_co_u32_e32 v33, vcc, 0, v53, vcc
	v_lshl_add_u64 v[32:33], v[56:57], 0, v[32:33]
	v_lshl_add_u64 v[34:35], v[32:33], 0, v[200:201]
	s_waitcnt lgkmcnt(0)
	v_add_f32_e32 v32, v36, v37
	v_mov_b32_e32 v33, v32
	s_nop 1
	v_permlane32_swap_b32_e32 v32, v33
	v_cvt_pk_fp8_f32 v40, v38, v39 op_sel:[0,0,1]
	v_cvt_pk_fp8_f32 v41, v48, v49 op_sel:[0,0,1]
	v_add_co_u32_e32 v34, vcc, s21, v34
	s_nop 1
	v_addc_co_u32_e32 v35, vcc, 0, v35, vcc
	global_store_dwordx2 v[34:35], v[40:41], off offset:128
	s_and_saveexec_b64 s[14:15], s[36:37]
	s_cbranch_execz .LBB0_437
	s_waitcnt lgkmcnt(0)
	v_add_f32_e32 v32, v32, v33
	v_fma_f32 v32, v32, s18, 0.5
	v_cvt_u32_f32_e32 v34, v32
	v_readlane_b32 s16, v253, 5
	v_readlane_b32 s17, v253, 6
	s_nop 1
	v_lshl_add_u64 v[32:33], v[210:211], 2, s[16:17]
	global_atomic_add v[32:33], v34, off
.LBB0_437:
	s_or_b64 exec, exec, s[14:15]
	v_lshlrev_b32_e32 v32, 16, v108
	s_waitcnt lgkmcnt(0)
	v_and_b32_e32 v33, 0xffff0000, v108
	v_lshlrev_b32_e32 v38, 16, v111
	v_and_b32_e32 v39, 0xffff0000, v111
	v_lshlrev_b32_e32 v36, 16, v110
	v_and_b32_e32 v37, 0xffff0000, v110
	v_pk_add_f32 v[28:29], v[28:29], v[32:33]
	v_pk_add_f32 v[26:27], v[26:27], v[38:39]
	v_lshlrev_b32_e32 v32, 16, v104
	v_and_b32_e32 v33, 0xffff0000, v104
	v_lshlrev_b32_e32 v38, 16, v107
	v_and_b32_e32 v39, 0xffff0000, v107
	v_pk_add_f32 v[24:25], v[24:25], v[36:37]
	v_pk_add_f32 v[20:21], v[20:21], v[32:33]
	v_pk_add_f32 v[32:33], v[18:19], v[38:39]
	v_mov_b32_e32 v38, 0
	v_mov_b32_e32 v39, 0
	v_cvt_pk_fp8_f32 v38, v28, v29
	v_cvt_pk_fp8_f32 v39, v24, v25
	v_lshlrev_b32_e32 v34, 16, v109
	v_and_b32_e32 v35, 0xffff0000, v109
	v_pk_add_f32 v[30:31], v[30:31], v[34:35]
	v_lshlrev_b32_e32 v34, 16, v105
	v_and_b32_e32 v35, 0xffff0000, v105
	v_lshlrev_b32_e32 v36, 16, v106
	v_and_b32_e32 v37, 0xffff0000, v106
	v_lshl_add_u64 v[40:41], s[64:65], 0, v[208:209]
	v_cvt_pk_fp8_f32 v38, v30, v31 op_sel:[0,0,1]
	v_cvt_pk_fp8_f32 v39, v26, v27 op_sel:[0,0,1]
	v_pk_add_f32 v[22:23], v[22:23], v[34:35]
	v_pk_add_f32 v[34:35], v[16:17], v[36:37]
	v_lshlrev_b64 v[36:37], 10, v[206:207]
	v_cvt_pk_bf16_f32 v16, v28, v29
	v_cvt_pk_bf16_f32 v17, v30, v31
	v_lshl_add_u64 v[42:43], v[200:201], 1, v[40:41]
	v_cvt_pk_bf16_f32 v18, v24, v25
	v_cvt_pk_bf16_f32 v19, v26, v27
	global_store_dwordx4 v[42:43], v[16:19], off
	s_nop 1
	v_lshl_add_u64 v[16:17], s[54:55], 0, v[36:37]
	v_lshl_add_u64 v[16:17], v[16:17], 0, v[200:201]
	global_store_dwordx2 v[16:17], v[38:39], off
	v_mul_f32_e32 v16, v29, v29
	v_mul_f32_e32 v17, v31, v31
	v_fmac_f32_e32 v16, v28, v28
	v_fmac_f32_e32 v17, v30, v30
	v_add_f32_e32 v16, v16, v17
	v_mul_f32_e32 v17, v25, v25
	v_fmac_f32_e32 v17, v24, v24
	v_add_f32_e32 v16, v17, v16
	v_mul_f32_e32 v17, v27, v27
	v_fmac_f32_e32 v17, v26, v26
	v_add_f32_e32 v26, v17, v16
	v_cvt_pk_bf16_f32 v16, v20, v21
	v_cvt_pk_bf16_f32 v17, v22, v23
	v_cvt_pk_bf16_f32 v18, v34, v35
	v_cvt_pk_bf16_f32 v19, v32, v33
	global_store_dwordx4 v[42:43], v[16:19], off offset:256
	v_mov_b32_e32 v24, 0
	v_cvt_pk_fp8_f32 v24, v20, v21
	v_mul_f32_e32 v16, v21, v21
	v_mul_f32_e32 v17, v23, v23
	v_fmac_f32_e32 v16, v20, v20
	v_fmac_f32_e32 v17, v22, v22
	v_add_f32_e32 v16, v16, v17
	v_mul_f32_e32 v17, v35, v35
	v_fmac_f32_e32 v17, v34, v34
	v_add_f32_e32 v16, v17, v16
	v_mul_f32_e32 v17, v33, v33
	v_fmac_f32_e32 v17, v32, v32
	v_add_f32_e32 v16, v17, v16
	v_add_f32_e32 v20, v26, v16
	v_mov_b32_e32 v21, v20
	s_nop 1
	v_permlane16_swap_b32_e32 v20, v21
	v_mov_b32_e32 v25, 0
	v_sub_co_u32_e32 v16, vcc, 0, v36
	v_cvt_pk_fp8_f32 v25, v34, v35
	s_nop 0
	v_subb_co_u32_e32 v17, vcc, 0, v37, vcc
	v_lshl_add_u64 v[16:17], v[40:41], 0, v[16:17]
	v_lshl_add_u64 v[18:19], v[16:17], 0, v[200:201]
	s_waitcnt lgkmcnt(0)
	v_add_f32_e32 v16, v20, v21
	v_mov_b32_e32 v17, v16
	s_nop 1
	v_permlane32_swap_b32_e32 v16, v17
	v_cvt_pk_fp8_f32 v24, v22, v23 op_sel:[0,0,1]
	v_cvt_pk_fp8_f32 v25, v32, v33 op_sel:[0,0,1]
	v_add_co_u32_e32 v18, vcc, s21, v18
	s_nop 1
	v_addc_co_u32_e32 v19, vcc, 0, v19, vcc
	global_store_dwordx2 v[18:19], v[24:25], off offset:128
	s_and_saveexec_b64 s[14:15], s[36:37]
	s_cbranch_execz .LBB0_439
	s_waitcnt lgkmcnt(0)
	v_add_f32_e32 v16, v16, v17
	v_fma_f32 v16, v16, s18, 0.5
	v_cvt_u32_f32_e32 v18, v16
	v_readlane_b32 s16, v253, 5
	v_readlane_b32 s17, v253, 6
	s_nop 1
	v_lshl_add_u64 v[16:17], v[206:207], 2, s[16:17]
	global_atomic_add v[16:17], v18, off
.LBB0_439:
	s_or_b64 exec, exec, s[14:15]
	v_lshlrev_b32_e32 v16, 16, v84
	s_waitcnt lgkmcnt(0)
	v_and_b32_e32 v17, 0xffff0000, v84
	v_lshlrev_b32_e32 v22, 16, v87
	v_and_b32_e32 v23, 0xffff0000, v87
	v_lshlrev_b32_e32 v20, 16, v86
	v_and_b32_e32 v21, 0xffff0000, v86
	v_pk_add_f32 v[12:13], v[12:13], v[16:17]
	v_pk_add_f32 v[10:11], v[10:11], v[22:23]
	v_lshlrev_b32_e32 v16, 16, v80
	v_and_b32_e32 v17, 0xffff0000, v80
	v_lshlrev_b32_e32 v22, 16, v83
	v_and_b32_e32 v23, 0xffff0000, v83
	v_pk_add_f32 v[8:9], v[8:9], v[20:21]
	v_pk_add_f32 v[4:5], v[4:5], v[16:17]
	v_pk_add_f32 v[16:17], v[2:3], v[22:23]
	v_mov_b32_e32 v22, 0
	v_mov_b32_e32 v23, 0
	v_cvt_pk_fp8_f32 v22, v12, v13
	v_cvt_pk_fp8_f32 v23, v8, v9
	v_lshlrev_b32_e32 v18, 16, v85
	v_and_b32_e32 v19, 0xffff0000, v85
	v_pk_add_f32 v[14:15], v[14:15], v[18:19]
	v_lshlrev_b32_e32 v18, 16, v81
	v_and_b32_e32 v19, 0xffff0000, v81
	v_lshlrev_b32_e32 v20, 16, v82
	v_and_b32_e32 v21, 0xffff0000, v82
	v_lshl_add_u64 v[24:25], s[64:65], 0, v[204:205]
	v_cvt_pk_fp8_f32 v22, v14, v15 op_sel:[0,0,1]
	v_cvt_pk_fp8_f32 v23, v10, v11 op_sel:[0,0,1]
	v_pk_add_f32 v[6:7], v[6:7], v[18:19]
	v_pk_add_f32 v[18:19], v[0:1], v[20:21]
	v_lshlrev_b64 v[20:21], 10, v[202:203]
	v_cvt_pk_bf16_f32 v0, v12, v13
	v_cvt_pk_bf16_f32 v1, v14, v15
	v_lshl_add_u64 v[26:27], v[200:201], 1, v[24:25]
	v_cvt_pk_bf16_f32 v2, v8, v9
	v_cvt_pk_bf16_f32 v3, v10, v11
	global_store_dwordx4 v[26:27], v[0:3], off
	s_nop 1
	v_lshl_add_u64 v[0:1], s[54:55], 0, v[20:21]
	v_lshl_add_u64 v[0:1], v[0:1], 0, v[200:201]
	global_store_dwordx2 v[0:1], v[22:23], off
	v_mul_f32_e32 v0, v13, v13
	v_mul_f32_e32 v1, v15, v15
	v_fmac_f32_e32 v0, v12, v12
	v_fmac_f32_e32 v1, v14, v14
	v_add_f32_e32 v0, v0, v1
	v_mul_f32_e32 v1, v9, v9
	v_fmac_f32_e32 v1, v8, v8
	v_add_f32_e32 v0, v1, v0
	v_mul_f32_e32 v1, v11, v11
	v_fmac_f32_e32 v1, v10, v10
	v_add_f32_e32 v10, v1, v0
	v_cvt_pk_bf16_f32 v0, v4, v5
	v_cvt_pk_bf16_f32 v1, v6, v7
	v_cvt_pk_bf16_f32 v2, v18, v19
	v_cvt_pk_bf16_f32 v3, v16, v17
	global_store_dwordx4 v[26:27], v[0:3], off offset:256
	v_mov_b32_e32 v8, 0
	v_cvt_pk_fp8_f32 v8, v4, v5
	v_mul_f32_e32 v0, v5, v5
	v_mul_f32_e32 v1, v7, v7
	v_fmac_f32_e32 v0, v4, v4
	v_fmac_f32_e32 v1, v6, v6
	v_add_f32_e32 v0, v0, v1
	v_mul_f32_e32 v1, v19, v19
	v_fmac_f32_e32 v1, v18, v18
	v_add_f32_e32 v0, v1, v0
	v_mul_f32_e32 v1, v17, v17
	v_fmac_f32_e32 v1, v16, v16
	v_add_f32_e32 v0, v1, v0
	v_add_f32_e32 v4, v10, v0
	v_mov_b32_e32 v5, v4
	s_nop 1
	v_permlane16_swap_b32_e32 v4, v5
	v_mov_b32_e32 v9, 0
	v_sub_co_u32_e32 v0, vcc, 0, v20
	v_cvt_pk_fp8_f32 v9, v18, v19
	s_nop 0
	v_subb_co_u32_e32 v1, vcc, 0, v21, vcc
	v_lshl_add_u64 v[0:1], v[24:25], 0, v[0:1]
	v_lshl_add_u64 v[2:3], v[0:1], 0, v[200:201]
	s_waitcnt lgkmcnt(0)
	v_add_f32_e32 v0, v4, v5
	v_mov_b32_e32 v1, v0
	s_nop 1
	v_permlane32_swap_b32_e32 v0, v1
	v_cvt_pk_fp8_f32 v8, v6, v7 op_sel:[0,0,1]
	v_cvt_pk_fp8_f32 v9, v16, v17 op_sel:[0,0,1]
	v_add_co_u32_e32 v2, vcc, s21, v2
	s_nop 1
	v_addc_co_u32_e32 v3, vcc, 0, v3, vcc
	global_store_dwordx2 v[2:3], v[8:9], off offset:128
	s_and_saveexec_b64 s[14:15], s[36:37]
	s_cbranch_execz .LBB0_441
	s_waitcnt lgkmcnt(0)
	v_add_f32_e32 v0, v0, v1
	v_fma_f32 v0, v0, s18, 0.5
	v_cvt_u32_f32_e32 v2, v0
	v_readlane_b32 s16, v253, 5
	v_readlane_b32 s17, v253, 6
	s_nop 1
	v_lshl_add_u64 v[0:1], v[202:203], 2, s[16:17]
	global_atomic_add v[0:1], v2, off
